# GEMM K-loop: redundant s_setprio 0/1 pair in the middle of each 32-MFMA segment removed (uninterrupted MFMA stream)
# baseline (speedup 1.0000x reference)
; #define PG8_STAGE(bufoff, gbase, voff) do { _Pragma("unroll") for (int _i = 0; _i < 2; ++_i) \
;         __builtin_amdgcn_global_load_lds((const unsigned*)((const char*)(gbase) + (voff)[_i]), (PG8_LAS unsigned*)(lds + (bufoff) + ldsw + _i * 8192), 16, 0, 0); } while (0)
; #define PG8_LDA(dst, b, h) do { _Pragma("unroll") for (int m = 0; m < 4; ++m) _Pragma("unroll") for (int k = 0; k < 2; ++k) dst[m][k] = *(const PG8_LAS bf16x8*)(lds + PG8_SA(b, h) + aoff + m * 2048 + k * 1024); } while (0)
; #define PG8_LDB(dst, b, h) do { _Pragma("unroll") for (int n = 0; n < 2; ++n) _Pragma("unroll") for (int k = 0; k < 2; ++k) dst[n][k] = *(const PG8_LAS bf16x8*)(lds + PG8_SB(b, h) + boff + n * 2048 + k * 1024); } while (0)
; #define PG8_MMA(ai, bj, At, Bt) do { __builtin_amdgcn_s_setprio(1); _Pragma("unroll") for (int m = 0; m < 4; ++m) _Pragma("unroll") for (int n = 0; n < 2; ++n) _Pragma("unroll") for (int k = 0; k < 2; ++k) \
;         acc[ai][bj][m][n] = __builtin_amdgcn_mfma_f32_16x16x32_bf16(Bt[n][k], At[m][k], acc[ai][bj][m][n], 0, 0, 0); __builtin_amdgcn_s_setprio(0); } while (0)
; #define PG8_WAIT_V(n) asm volatile("s_waitcnt vmcnt(" #n ")" ::: "memory")
; #define PG8_WAIT_L(n) asm volatile("s_waitcnt lgkmcnt(" #n ")" ::: "memory")
; #define PG8_BAR __builtin_amdgcn_s_barrier()
; #define PG8_SCHED __builtin_amdgcn_sched_barrier(0)
; template <class Epi, class Sched, bool ALIGN_EPI = false, bool SP2 = false>
; __device__ __forceinline__ void gemm_phase(PG8_LAS unsigned char* lds, const Gemm g, const Sched& S, const Epi& E) {
;     ...
;             PG8_LDB(B0, 0, 0); PG8_LDB(B1, 0, 1); PG8_SCHED; PG8_LDA(At, 0, 0); PG8_STAGE(PG8_SA(1, 1), a1 + hstep, voffA);
;             PG8_WAIT_V(8); PG8_WAIT_L(0); PG8_BAR; PG8_MMA(0, 0, At, B0); PG8_MMA(0, 1, At, B1); PG8_BAR; PG8_SCHED;
;             PG8_LDA(At, 0, 1); PG8_STAGE(PG8_SB(0, 0), b2, voffB); PG8_STAGE(PG8_SB(0, 1), b2 + hstep, voffB); PG8_STAGE(PG8_SA(0, 0), a2, voffA);
;             PG8_WAIT_V(8); PG8_WAIT_L(0); PG8_BAR; PG8_MMA(1, 0, At, B0); PG8_MMA(1, 1, At, B1); PG8_BAR; PG8_SCHED;
.LBB0_76:
	s_add_u32 s36, s10, 0xfff80080
	s_addc_u32 s37, s11, -1
	s_add_i32 s64, 0, 0x10000
	s_cmp_eq_u32 s63, 28
	s_cselect_b32 s39, s29, s37
	s_cselect_b32 s38, s57, s36
	v_add_u32_e32 v1, s64, v153
	s_cselect_b32 s37, s27, s62
	s_cselect_b32 s36, s58, s59
	s_add_i32 s66, 0, 0x14000
	ds_read_b128 v[142:145], v1
	ds_read_b128 v[146:149], v1 offset:1024
	ds_read_b128 v[156:159], v1 offset:2048
	ds_read_b128 v[160:163], v1 offset:3072
	v_add_u32_e32 v1, s66, v153
	ds_read_b128 v[168:171], v1
	ds_read_b128 v[172:175], v1 offset:1024
	ds_read_b128 v[176:179], v1 offset:2048
	ds_read_b128 v[180:183], v1 offset:3072
	v_lshl_add_u64 v[150:151], s[10:11], 0, v[138:139]
	s_add_i32 m0, s43, 0xc000
	ds_read_b128 v[184:187], v155
	ds_read_b128 v[188:191], v155 offset:1024
	ds_read_b128 v[192:195], v155 offset:2048
	ds_read_b128 v[196:199], v155 offset:3072
	ds_read_b128 v[200:203], v155 offset:4096
	ds_read_b128 v[204:207], v155 offset:5120
	ds_read_b128 v[208:211], v155 offset:6144
	ds_read_b128 v[218:221], v155 offset:7168
	global_load_lds_dwordx4 v[150:151], off
	v_lshl_add_u64 v[150:151], s[10:11], 0, v[140:141]
	s_add_i32 m0, s43, 0xe000
	s_nop 0
	global_load_lds_dwordx4 v[150:151], off
	s_waitcnt vmcnt(8)
	s_waitcnt lgkmcnt(0)
	s_barrier
	s_setprio 1
	s_waitcnt lgkmcnt(0)
	v_mfma_f32_16x16x32_bf16 v[126:129], v[142:145], v[184:187], v[126:129]
	v_mfma_f32_16x16x32_bf16 v[122:125], v[156:159], v[184:187], v[122:125]
	v_mfma_f32_16x16x32_bf16 v[110:113], v[142:145], v[192:195], v[110:113]
	v_mfma_f32_16x16x32_bf16 v[106:109], v[156:159], v[192:195], v[106:109]
	v_mfma_f32_16x16x32_bf16 v[94:97], v[142:145], v[200:203], v[94:97]
	v_mfma_f32_16x16x32_bf16 v[90:93], v[156:159], v[200:203], v[90:93]
	v_mfma_f32_16x16x32_bf16 v[78:81], v[142:145], v[208:211], v[78:81]
	v_mfma_f32_16x16x32_bf16 v[74:77], v[156:159], v[208:211], v[74:77]
	v_mfma_f32_16x16x32_bf16 v[126:129], v[146:149], v[188:191], v[126:129]
	v_mfma_f32_16x16x32_bf16 v[122:125], v[160:163], v[188:191], v[122:125]
	v_mfma_f32_16x16x32_bf16 v[110:113], v[146:149], v[196:199], v[110:113]
	v_mfma_f32_16x16x32_bf16 v[106:109], v[160:163], v[196:199], v[106:109]
	v_mfma_f32_16x16x32_bf16 v[94:97], v[146:149], v[204:207], v[94:97]
	v_mfma_f32_16x16x32_bf16 v[90:93], v[160:163], v[204:207], v[90:93]
	v_mfma_f32_16x16x32_bf16 v[78:81], v[146:149], v[218:221], v[78:81]
	v_mfma_f32_16x16x32_bf16 v[74:77], v[160:163], v[218:221], v[74:77]
	v_mfma_f32_16x16x32_bf16 v[118:121], v[168:171], v[184:187], v[118:121]
	v_mfma_f32_16x16x32_bf16 v[114:117], v[176:179], v[184:187], v[114:117]
	v_mfma_f32_16x16x32_bf16 v[102:105], v[168:171], v[192:195], v[102:105]
	v_mfma_f32_16x16x32_bf16 v[98:101], v[176:179], v[192:195], v[98:101]
	v_mfma_f32_16x16x32_bf16 v[86:89], v[168:171], v[200:203], v[86:89]
	v_mfma_f32_16x16x32_bf16 v[82:85], v[176:179], v[200:203], v[82:85]
	v_mfma_f32_16x16x32_bf16 v[70:73], v[168:171], v[208:211], v[70:73]
	v_mfma_f32_16x16x32_bf16 v[66:69], v[176:179], v[208:211], v[66:69]
	v_mfma_f32_16x16x32_bf16 v[118:121], v[172:175], v[188:191], v[118:121]
	v_mfma_f32_16x16x32_bf16 v[114:117], v[180:183], v[188:191], v[114:117]
	v_mfma_f32_16x16x32_bf16 v[102:105], v[172:175], v[196:199], v[102:105]
	v_mfma_f32_16x16x32_bf16 v[98:101], v[180:183], v[196:199], v[98:101]
	v_mfma_f32_16x16x32_bf16 v[86:89], v[172:175], v[204:207], v[86:89]
	v_mfma_f32_16x16x32_bf16 v[82:85], v[180:183], v[204:207], v[82:85]
	v_mfma_f32_16x16x32_bf16 v[70:73], v[172:175], v[218:221], v[70:73]
	v_mfma_f32_16x16x32_bf16 v[66:69], v[180:183], v[218:221], v[66:69]
	s_setprio 0
	s_barrier
	s_add_i32 s64, s64, s42
	v_lshl_add_u64 v[150:151], s[36:37], 0, v[134:135]
	s_mov_b32 m0, s64
	ds_read_b128 v[184:187], v155 offset:16384
	ds_read_b128 v[188:191], v155 offset:17408
	ds_read_b128 v[192:195], v155 offset:18432
	ds_read_b128 v[196:199], v155 offset:19456
	ds_read_b128 v[200:203], v155 offset:20480
	ds_read_b128 v[204:207], v155 offset:21504
	ds_read_b128 v[208:211], v155 offset:22528
	ds_read_b128 v[218:221], v155 offset:23552
	global_load_lds_dwordx4 v[150:151], off
	s_add_i32 m0, s64, 0x2000
	s_add_u32 s64, s36, 0x80000
	v_lshl_add_u64 v[212:213], s[36:37], 0, v[130:131]
	s_addc_u32 s65, s37, 0
	s_add_i32 s66, s66, s42
	global_load_lds_dwordx4 v[212:213], off
	v_lshl_add_u64 v[226:227], s[64:65], 0, v[134:135]
	s_mov_b32 m0, s66
	v_lshl_add_u64 v[228:229], s[38:39], 0, v[132:133]
	global_load_lds_dwordx4 v[226:227], off
	v_lshl_add_u64 v[226:227], s[64:65], 0, v[130:131]
	s_add_i32 m0, s66, 0x2000
	s_nop 0
	global_load_lds_dwordx4 v[226:227], off
	v_lshl_add_u64 v[226:227], s[38:39], 0, v[136:137]
	s_mov_b32 m0, s43
	s_nop 0
	global_load_lds_dwordx4 v[226:227], off
	s_mov_b32 m0, s44
	s_nop 0
	global_load_lds_dwordx4 v[228:229], off
	s_waitcnt vmcnt(8)
	s_waitcnt lgkmcnt(0)
	s_barrier
; #define PG8_STAGE(bufoff, gbase, voff) do { _Pragma("unroll") for (int _i = 0; _i < 2; ++_i) \
;         __builtin_amdgcn_global_load_lds((const unsigned*)((const char*)(gbase) + (voff)[_i]), (PG8_LAS unsigned*)(lds + (bufoff) + ldsw + _i * 8192), 16, 0, 0); } while (0)
; #define PG8_LDA(dst, b, h) do { _Pragma("unroll") for (int m = 0; m < 4; ++m) _Pragma("unroll") for (int k = 0; k < 2; ++k) dst[m][k] = *(const PG8_LAS bf16x8*)(lds + PG8_SA(b, h) + aoff + m * 2048 + k * 1024); } while (0)
; #define PG8_LDB(dst, b, h) do { _Pragma("unroll") for (int n = 0; n < 2; ++n) _Pragma("unroll") for (int k = 0; k < 2; ++k) dst[n][k] = *(const PG8_LAS bf16x8*)(lds + PG8_SB(b, h) + boff + n * 2048 + k * 1024); } while (0)
; #define PG8_MMA(ai, bj, At, Bt) do { __builtin_amdgcn_s_setprio(1); _Pragma("unroll") for (int m = 0; m < 4; ++m) _Pragma("unroll") for (int n = 0; n < 2; ++n) _Pragma("unroll") for (int k = 0; k < 2; ++k) \
;         acc[ai][bj][m][n] = __builtin_amdgcn_mfma_f32_16x16x32_bf16(Bt[n][k], At[m][k], acc[ai][bj][m][n], 0, 0, 0); __builtin_amdgcn_s_setprio(0); } while (0)
; #define PG8_WAIT_V(n) asm volatile("s_waitcnt vmcnt(" #n ")" ::: "memory")
; #define PG8_WAIT_L(n) asm volatile("s_waitcnt lgkmcnt(" #n ")" ::: "memory")
; #define PG8_BAR __builtin_amdgcn_s_barrier()
; #define PG8_SCHED __builtin_amdgcn_sched_barrier(0)
; template <class Epi, class Sched, bool ALIGN_EPI = false, bool SP2 = false>
; __device__ __forceinline__ void gemm_phase(PG8_LAS unsigned char* lds, const Gemm g, const Sched& S, const Epi& E) {
;     ...
;             PG8_WAIT_V(8); PG8_WAIT_L(0); PG8_BAR; PG8_MMA(1, 0, At, B0); PG8_MMA(1, 1, At, B1); PG8_BAR; PG8_SCHED;
;             PG8_LDB(B0, 1, 0); PG8_LDB(B1, 1, 1); PG8_SCHED; PG8_LDA(At, 1, 0); PG8_STAGE(PG8_SA(0, 1), a2 + hstep, voffA);
;             PG8_WAIT_V(8); PG8_WAIT_L(0); PG8_BAR; PG8_MMA(0, 0, At, B0); PG8_MMA(0, 1, At, B1); PG8_BAR; PG8_SCHED;
	s_setprio 1
	s_waitcnt lgkmcnt(0)
	v_mfma_f32_16x16x32_bf16 v[62:65], v[142:145], v[184:187], v[62:65]
	v_mfma_f32_16x16x32_bf16 v[58:61], v[156:159], v[184:187], v[58:61]
	v_mfma_f32_16x16x32_bf16 v[46:49], v[142:145], v[192:195], v[46:49]
	v_mfma_f32_16x16x32_bf16 v[42:45], v[156:159], v[192:195], v[42:45]
	v_mfma_f32_16x16x32_bf16 v[30:33], v[142:145], v[200:203], v[30:33]
	v_mfma_f32_16x16x32_bf16 v[26:29], v[156:159], v[200:203], v[26:29]
	v_mfma_f32_16x16x32_bf16 v[14:17], v[142:145], v[208:211], v[14:17]
	v_mfma_f32_16x16x32_bf16 v[10:13], v[156:159], v[208:211], v[10:13]
	v_mfma_f32_16x16x32_bf16 v[62:65], v[146:149], v[188:191], v[62:65]
	v_mfma_f32_16x16x32_bf16 v[58:61], v[160:163], v[188:191], v[58:61]
	v_mfma_f32_16x16x32_bf16 v[46:49], v[146:149], v[196:199], v[46:49]
	v_mfma_f32_16x16x32_bf16 v[42:45], v[160:163], v[196:199], v[42:45]
	v_mfma_f32_16x16x32_bf16 v[30:33], v[146:149], v[204:207], v[30:33]
	v_mfma_f32_16x16x32_bf16 v[26:29], v[160:163], v[204:207], v[26:29]
	v_mfma_f32_16x16x32_bf16 v[14:17], v[146:149], v[218:221], v[14:17]
	v_mfma_f32_16x16x32_bf16 v[10:13], v[160:163], v[218:221], v[10:13]
	v_mfma_f32_16x16x32_bf16 v[54:57], v[168:171], v[184:187], v[54:57]
	v_mfma_f32_16x16x32_bf16 v[50:53], v[176:179], v[184:187], v[50:53]
	v_mfma_f32_16x16x32_bf16 v[38:41], v[168:171], v[192:195], v[38:41]
	v_mfma_f32_16x16x32_bf16 v[34:37], v[176:179], v[192:195], v[34:37]
	v_mfma_f32_16x16x32_bf16 v[22:25], v[168:171], v[200:203], v[22:25]
	v_mfma_f32_16x16x32_bf16 v[18:21], v[176:179], v[200:203], v[18:21]
	v_mfma_f32_16x16x32_bf16 v[6:9], v[168:171], v[208:211], v[6:9]
	v_mfma_f32_16x16x32_bf16 v[2:5], v[176:179], v[208:211], v[2:5]
	v_mfma_f32_16x16x32_bf16 v[54:57], v[172:175], v[188:191], v[54:57]
	v_mfma_f32_16x16x32_bf16 v[50:53], v[180:183], v[188:191], v[50:53]
	v_mfma_f32_16x16x32_bf16 v[38:41], v[172:175], v[196:199], v[38:41]
	v_mfma_f32_16x16x32_bf16 v[34:37], v[180:183], v[196:199], v[34:37]
	v_mfma_f32_16x16x32_bf16 v[22:25], v[172:175], v[204:207], v[22:25]
	v_mfma_f32_16x16x32_bf16 v[18:21], v[180:183], v[204:207], v[18:21]
	v_mfma_f32_16x16x32_bf16 v[6:9], v[172:175], v[218:221], v[6:9]
	v_mfma_f32_16x16x32_bf16 v[2:5], v[180:183], v[218:221], v[2:5]
	s_setprio 0
	s_barrier
	s_add_i32 s64, 0, 0x18000
	v_add_u32_e32 v1, s64, v153
	s_add_i32 s65, 0, 0x1c000
	ds_read_b128 v[142:145], v1
	ds_read_b128 v[146:149], v1 offset:1024
	ds_read_b128 v[156:159], v1 offset:2048
	ds_read_b128 v[160:163], v1 offset:3072
	v_add_u32_e32 v1, s65, v153
	ds_read_b128 v[168:171], v1
	ds_read_b128 v[172:175], v1 offset:1024
	ds_read_b128 v[176:179], v1 offset:2048
	ds_read_b128 v[180:183], v1 offset:3072
	s_add_u32 s38, s38, 0x80000
	s_addc_u32 s39, s39, 0
	s_mov_b32 m0, s45
	v_lshl_add_u64 v[230:231], s[38:39], 0, v[136:137]
	ds_read_b128 v[184:187], v155 offset:32768
	ds_read_b128 v[188:191], v155 offset:33792
	ds_read_b128 v[192:195], v155 offset:34816
	ds_read_b128 v[196:199], v155 offset:35840
	ds_read_b128 v[200:203], v155 offset:36864
	ds_read_b128 v[204:207], v155 offset:37888
	ds_read_b128 v[208:211], v155 offset:38912
	ds_read_b128 v[218:221], v155 offset:39936
	global_load_lds_dwordx4 v[230:231], off
	v_lshl_add_u64 v[230:231], s[38:39], 0, v[132:133]
	s_mov_b32 m0, s46
	s_nop 0
	global_load_lds_dwordx4 v[230:231], off
	s_waitcnt vmcnt(8)
	s_waitcnt lgkmcnt(0)
	s_barrier
	s_setprio 1
	s_waitcnt lgkmcnt(0)
	v_mfma_f32_16x16x32_bf16 v[126:129], v[142:145], v[184:187], v[126:129]
	v_mfma_f32_16x16x32_bf16 v[122:125], v[156:159], v[184:187], v[122:125]
	v_mfma_f32_16x16x32_bf16 v[110:113], v[142:145], v[192:195], v[110:113]
	v_mfma_f32_16x16x32_bf16 v[106:109], v[156:159], v[192:195], v[106:109]
	v_mfma_f32_16x16x32_bf16 v[94:97], v[142:145], v[200:203], v[94:97]
	v_mfma_f32_16x16x32_bf16 v[90:93], v[156:159], v[200:203], v[90:93]
	v_mfma_f32_16x16x32_bf16 v[78:81], v[142:145], v[208:211], v[78:81]
	v_mfma_f32_16x16x32_bf16 v[74:77], v[156:159], v[208:211], v[74:77]
	v_mfma_f32_16x16x32_bf16 v[126:129], v[146:149], v[188:191], v[126:129]
	v_mfma_f32_16x16x32_bf16 v[122:125], v[160:163], v[188:191], v[122:125]
	v_mfma_f32_16x16x32_bf16 v[110:113], v[146:149], v[196:199], v[110:113]
	v_mfma_f32_16x16x32_bf16 v[106:109], v[160:163], v[196:199], v[106:109]
	v_mfma_f32_16x16x32_bf16 v[94:97], v[146:149], v[204:207], v[94:97]
	v_mfma_f32_16x16x32_bf16 v[90:93], v[160:163], v[204:207], v[90:93]
	v_mfma_f32_16x16x32_bf16 v[78:81], v[146:149], v[218:221], v[78:81]
	v_mfma_f32_16x16x32_bf16 v[74:77], v[160:163], v[218:221], v[74:77]
	v_mfma_f32_16x16x32_bf16 v[118:121], v[168:171], v[184:187], v[118:121]
	v_mfma_f32_16x16x32_bf16 v[114:117], v[176:179], v[184:187], v[114:117]
	v_mfma_f32_16x16x32_bf16 v[102:105], v[168:171], v[192:195], v[102:105]
	v_mfma_f32_16x16x32_bf16 v[98:101], v[176:179], v[192:195], v[98:101]
	v_mfma_f32_16x16x32_bf16 v[86:89], v[168:171], v[200:203], v[86:89]
	v_mfma_f32_16x16x32_bf16 v[82:85], v[176:179], v[200:203], v[82:85]
	v_mfma_f32_16x16x32_bf16 v[70:73], v[168:171], v[208:211], v[70:73]
	v_mfma_f32_16x16x32_bf16 v[66:69], v[176:179], v[208:211], v[66:69]
	v_mfma_f32_16x16x32_bf16 v[118:121], v[172:175], v[188:191], v[118:121]
	v_mfma_f32_16x16x32_bf16 v[114:117], v[180:183], v[188:191], v[114:117]
	v_mfma_f32_16x16x32_bf16 v[102:105], v[172:175], v[196:199], v[102:105]
	v_mfma_f32_16x16x32_bf16 v[98:101], v[180:183], v[196:199], v[98:101]
	v_mfma_f32_16x16x32_bf16 v[86:89], v[172:175], v[204:207], v[86:89]
	v_mfma_f32_16x16x32_bf16 v[82:85], v[180:183], v[204:207], v[82:85]
	v_mfma_f32_16x16x32_bf16 v[70:73], v[172:175], v[218:221], v[70:73]
	v_mfma_f32_16x16x32_bf16 v[66:69], v[180:183], v[218:221], v[66:69]
	s_setprio 0
	s_barrier
; #define PG8_STAGE(bufoff, gbase, voff) do { _Pragma("unroll") for (int _i = 0; _i < 2; ++_i) \
;         __builtin_amdgcn_global_load_lds((const unsigned*)((const char*)(gbase) + (voff)[_i]), (PG8_LAS unsigned*)(lds + (bufoff) + ldsw + _i * 8192), 16, 0, 0); } while (0)
; #define PG8_LDA(dst, b, h) do { _Pragma("unroll") for (int m = 0; m < 4; ++m) _Pragma("unroll") for (int k = 0; k < 2; ++k) dst[m][k] = *(const PG8_LAS bf16x8*)(lds + PG8_SA(b, h) + aoff + m * 2048 + k * 1024); } while (0)
; #define PG8_MMA(ai, bj, At, Bt) do { __builtin_amdgcn_s_setprio(1); _Pragma("unroll") for (int m = 0; m < 4; ++m) _Pragma("unroll") for (int n = 0; n < 2; ++n) _Pragma("unroll") for (int k = 0; k < 2; ++k) \
;         acc[ai][bj][m][n] = __builtin_amdgcn_mfma_f32_16x16x32_bf16(Bt[n][k], At[m][k], acc[ai][bj][m][n], 0, 0, 0); __builtin_amdgcn_s_setprio(0); } while (0)
; #define PG8_WAIT_V(n) asm volatile("s_waitcnt vmcnt(" #n ")" ::: "memory")
; #define PG8_WAIT_L(n) asm volatile("s_waitcnt lgkmcnt(" #n ")" ::: "memory")
; #define PG8_BAR __builtin_amdgcn_s_barrier()
; #define PG8_SCHED __builtin_amdgcn_sched_barrier(0)
; template <class Epi, class Sched, bool ALIGN_EPI = false, bool SP2 = false>
; __device__ __forceinline__ void gemm_phase(PG8_LAS unsigned char* lds, const Gemm g, const Sched& S, const Epi& E) {
;     ...
;         for (int t = 0; t < nt; t += 2) {
;     ...
;             PG8_LDA(At, 1, 1); PG8_STAGE(PG8_SB(1, 0), b3, voffB); PG8_STAGE(PG8_SB(1, 1), b3 + hstep, voffB); PG8_STAGE(PG8_SA(1, 0), a3, voffA);
;             PG8_WAIT_V(8); PG8_WAIT_L(0); PG8_BAR; PG8_MMA(1, 0, At, B0); PG8_MMA(1, 1, At, B1); PG8_BAR; PG8_SCHED;
	s_add_i32 s38, s64, s42
	v_lshl_add_u64 v[150:151], v[150:151], 0, s[84:85]
	s_mov_b32 m0, s38
	ds_read_b128 v[184:187], v155 offset:49152
	ds_read_b128 v[188:191], v155 offset:50176
	ds_read_b128 v[192:195], v155 offset:51200
	ds_read_b128 v[196:199], v155 offset:52224
	ds_read_b128 v[200:203], v155 offset:53248
	ds_read_b128 v[204:207], v155 offset:54272
	ds_read_b128 v[208:211], v155 offset:55296
	ds_read_b128 v[218:221], v155 offset:56320
	global_load_lds_dwordx4 v[150:151], off
	s_add_i32 m0, s38, 0x2000
	s_add_u32 s36, s36, 0x80080
	v_lshl_add_u64 v[150:151], v[212:213], 0, s[84:85]
	s_addc_u32 s37, s37, 0
	s_add_i32 s38, s65, s42
	global_load_lds_dwordx4 v[150:151], off
	v_lshl_add_u64 v[150:151], s[36:37], 0, v[134:135]
	s_mov_b32 m0, s38
	s_nop 0
	global_load_lds_dwordx4 v[150:151], off
	v_lshl_add_u64 v[150:151], s[36:37], 0, v[130:131]
	s_add_i32 m0, s38, 0x2000
	s_nop 0
	global_load_lds_dwordx4 v[150:151], off
	v_lshl_add_u64 v[150:151], v[226:227], 0, s[84:85]
	s_mov_b32 m0, s47
	s_nop 0
	global_load_lds_dwordx4 v[150:151], off
	v_lshl_add_u64 v[150:151], v[228:229], 0, s[84:85]
	s_mov_b32 m0, s51
	s_nop 0
	global_load_lds_dwordx4 v[150:151], off
	s_waitcnt vmcnt(8)
	s_waitcnt lgkmcnt(0)
	s_barrier
	s_setprio 1
	s_waitcnt lgkmcnt(0)
	v_mfma_f32_16x16x32_bf16 v[62:65], v[142:145], v[184:187], v[62:65]
	v_mfma_f32_16x16x32_bf16 v[58:61], v[156:159], v[184:187], v[58:61]
	v_mfma_f32_16x16x32_bf16 v[46:49], v[142:145], v[192:195], v[46:49]
	v_mfma_f32_16x16x32_bf16 v[42:45], v[156:159], v[192:195], v[42:45]
	v_mfma_f32_16x16x32_bf16 v[30:33], v[142:145], v[200:203], v[30:33]
	v_mfma_f32_16x16x32_bf16 v[26:29], v[156:159], v[200:203], v[26:29]
	v_mfma_f32_16x16x32_bf16 v[14:17], v[142:145], v[208:211], v[14:17]
	v_mfma_f32_16x16x32_bf16 v[10:13], v[156:159], v[208:211], v[10:13]
	v_mfma_f32_16x16x32_bf16 v[62:65], v[146:149], v[188:191], v[62:65]
	v_mfma_f32_16x16x32_bf16 v[58:61], v[160:163], v[188:191], v[58:61]
	v_mfma_f32_16x16x32_bf16 v[46:49], v[146:149], v[196:199], v[46:49]
	v_mfma_f32_16x16x32_bf16 v[42:45], v[160:163], v[196:199], v[42:45]
	v_mfma_f32_16x16x32_bf16 v[30:33], v[146:149], v[204:207], v[30:33]
	v_mfma_f32_16x16x32_bf16 v[26:29], v[160:163], v[204:207], v[26:29]
	v_mfma_f32_16x16x32_bf16 v[14:17], v[146:149], v[218:221], v[14:17]
	v_mfma_f32_16x16x32_bf16 v[10:13], v[160:163], v[218:221], v[10:13]
	v_mfma_f32_16x16x32_bf16 v[54:57], v[168:171], v[184:187], v[54:57]
	v_mfma_f32_16x16x32_bf16 v[50:53], v[176:179], v[184:187], v[50:53]
	v_mfma_f32_16x16x32_bf16 v[38:41], v[168:171], v[192:195], v[38:41]
	v_mfma_f32_16x16x32_bf16 v[34:37], v[176:179], v[192:195], v[34:37]
	v_mfma_f32_16x16x32_bf16 v[22:25], v[168:171], v[200:203], v[22:25]
	v_mfma_f32_16x16x32_bf16 v[18:21], v[176:179], v[200:203], v[18:21]
	v_mfma_f32_16x16x32_bf16 v[6:9], v[168:171], v[208:211], v[6:9]
	v_mfma_f32_16x16x32_bf16 v[2:5], v[176:179], v[208:211], v[2:5]
	v_mfma_f32_16x16x32_bf16 v[54:57], v[172:175], v[188:191], v[54:57]
	v_mfma_f32_16x16x32_bf16 v[50:53], v[180:183], v[188:191], v[50:53]
	v_mfma_f32_16x16x32_bf16 v[38:41], v[172:175], v[196:199], v[38:41]
	v_mfma_f32_16x16x32_bf16 v[34:37], v[180:183], v[196:199], v[34:37]
	v_mfma_f32_16x16x32_bf16 v[22:25], v[172:175], v[204:207], v[22:25]
	v_mfma_f32_16x16x32_bf16 v[18:21], v[180:183], v[204:207], v[18:21]
	v_mfma_f32_16x16x32_bf16 v[6:9], v[172:175], v[218:221], v[6:9]
	v_mfma_f32_16x16x32_bf16 v[2:5], v[180:183], v[218:221], v[2:5]
	s_setprio 0
	s_barrier
	s_add_i32 s63, s63, 2
	s_add_u32 s10, s10, 0x100
	s_addc_u32 s11, s11, 0
	s_add_u32 s59, s59, 0x100
	s_addc_u32 s62, s62, 0
	s_cmp_gt_u32 s63, 29
	s_cbranch_scc0 .LBB0_76
	s_and_b64 vcc, exec, s[24:25]
	s_cbranch_vccz .LBB0_79
	s_barrier

; #define PG8_STAGE(bufoff, gbase, voff) do { _Pragma("unroll") for (int _i = 0; _i < 2; ++_i) \
;         __builtin_amdgcn_global_load_lds((const unsigned*)((const char*)(gbase) + (voff)[_i]), (PG8_LAS unsigned*)(lds + (bufoff) + ldsw + _i * 8192), 16, 0, 0); } while (0)
; #define PG8_LDA(dst, b, h) do { _Pragma("unroll") for (int m = 0; m < 4; ++m) _Pragma("unroll") for (int k = 0; k < 2; ++k) dst[m][k] = *(const PG8_LAS bf16x8*)(lds + PG8_SA(b, h) + aoff + m * 2048 + k * 1024); } while (0)
; #define PG8_LDB(dst, b, h) do { _Pragma("unroll") for (int n = 0; n < 2; ++n) _Pragma("unroll") for (int k = 0; k < 2; ++k) dst[n][k] = *(const PG8_LAS bf16x8*)(lds + PG8_SB(b, h) + boff + n * 2048 + k * 1024); } while (0)
; #define PG8_MMA(ai, bj, At, Bt) do { __builtin_amdgcn_s_setprio(1); _Pragma("unroll") for (int m = 0; m < 4; ++m) _Pragma("unroll") for (int n = 0; n < 2; ++n) _Pragma("unroll") for (int k = 0; k < 2; ++k) \
;         acc[ai][bj][m][n] = __builtin_amdgcn_mfma_f32_16x16x32_bf16(Bt[n][k], At[m][k], acc[ai][bj][m][n], 0, 0, 0); __builtin_amdgcn_s_setprio(0); } while (0)
; #define PG8_WAIT_V(n) asm volatile("s_waitcnt vmcnt(" #n ")" ::: "memory")
; #define PG8_WAIT_L(n) asm volatile("s_waitcnt lgkmcnt(" #n ")" ::: "memory")
; #define PG8_BAR __builtin_amdgcn_s_barrier()
; #define PG8_SCHED __builtin_amdgcn_sched_barrier(0)
; template <class Epi, class Sched, bool ALIGN_EPI = false, bool SP2 = false>
; __device__ __forceinline__ void gemm_phase(PG8_LAS unsigned char* lds, const Gemm g, const Sched& S, const Epi& E) {
;     ...
;             PG8_LDB(B0, 0, 0); PG8_LDB(B1, 0, 1); PG8_SCHED; PG8_LDA(At, 0, 0); PG8_STAGE(PG8_SA(1, 1), a1 + hstep, voffA);
;             PG8_WAIT_V(8); PG8_WAIT_L(0); PG8_BAR; PG8_MMA(0, 0, At, B0); PG8_MMA(0, 1, At, B1); PG8_BAR; PG8_SCHED;
;             PG8_LDA(At, 0, 1); PG8_STAGE(PG8_SB(0, 0), b2, voffB); PG8_STAGE(PG8_SB(0, 1), b2 + hstep, voffB); PG8_STAGE(PG8_SA(0, 0), a2, voffA);
;             PG8_WAIT_V(8); PG8_WAIT_L(0); PG8_BAR; PG8_MMA(1, 0, At, B0); PG8_MMA(1, 1, At, B1); PG8_BAR; PG8_SCHED;
.LBB0_133:
	s_add_u32 s28, s26, 0xfff80080
	s_addc_u32 s29, s27, -1
	s_add_i32 s55, 0, 0x10000
	s_cmp_eq_u32 s54, 28
	s_cselect_b32 s31, s21, s29
	s_cselect_b32 s30, s46, s28
	v_add_u32_e32 v149, s55, v146
	s_cselect_b32 s29, s19, s52
	s_cselect_b32 s28, s47, s51
	s_add_i32 s57, 0, 0x14000
	ds_read_b128 v[142:145], v149
	ds_read_b128 v[150:153], v149 offset:1024
	ds_read_b128 v[154:157], v149 offset:2048
	ds_read_b128 v[158:161], v149 offset:3072
	v_add_u32_e32 v149, s57, v146
	ds_read_b128 v[168:171], v149
	ds_read_b128 v[172:175], v149 offset:1024
	ds_read_b128 v[176:179], v149 offset:2048
	ds_read_b128 v[180:183], v149 offset:3072
	v_lshl_add_u64 v[162:163], s[26:27], 0, v[138:139]
	s_add_i32 m0, s37, 0xc000
	ds_read_b128 v[184:187], v148
	ds_read_b128 v[188:191], v148 offset:1024
	ds_read_b128 v[192:195], v148 offset:2048
	ds_read_b128 v[196:199], v148 offset:3072
	ds_read_b128 v[200:203], v148 offset:4096
	ds_read_b128 v[204:207], v148 offset:5120
	ds_read_b128 v[208:211], v148 offset:6144
	ds_read_b128 v[218:221], v148 offset:7168
	global_load_lds_dwordx4 v[162:163], off
	v_lshl_add_u64 v[162:163], s[26:27], 0, v[140:141]
	s_add_i32 m0, s37, 0xe000
	s_nop 0
	global_load_lds_dwordx4 v[162:163], off
	s_waitcnt vmcnt(8)
	s_waitcnt lgkmcnt(0)
	s_barrier
	s_setprio 1
	s_waitcnt lgkmcnt(0)
	v_mfma_f32_16x16x32_bf16 v[126:129], v[142:145], v[184:187], v[126:129]
	v_mfma_f32_16x16x32_bf16 v[118:121], v[154:157], v[184:187], v[118:121]
	v_mfma_f32_16x16x32_bf16 v[110:113], v[142:145], v[192:195], v[110:113]
	v_mfma_f32_16x16x32_bf16 v[102:105], v[154:157], v[192:195], v[102:105]
	v_mfma_f32_16x16x32_bf16 v[94:97], v[142:145], v[200:203], v[94:97]
	v_mfma_f32_16x16x32_bf16 v[86:89], v[154:157], v[200:203], v[86:89]
	v_mfma_f32_16x16x32_bf16 v[78:81], v[142:145], v[208:211], v[78:81]
	v_mfma_f32_16x16x32_bf16 v[70:73], v[154:157], v[208:211], v[70:73]
	v_mfma_f32_16x16x32_bf16 v[126:129], v[150:153], v[188:191], v[126:129]
	v_mfma_f32_16x16x32_bf16 v[118:121], v[158:161], v[188:191], v[118:121]
	v_mfma_f32_16x16x32_bf16 v[110:113], v[150:153], v[196:199], v[110:113]
	v_mfma_f32_16x16x32_bf16 v[102:105], v[158:161], v[196:199], v[102:105]
	v_mfma_f32_16x16x32_bf16 v[94:97], v[150:153], v[204:207], v[94:97]
	v_mfma_f32_16x16x32_bf16 v[86:89], v[158:161], v[204:207], v[86:89]
	v_mfma_f32_16x16x32_bf16 v[78:81], v[150:153], v[218:221], v[78:81]
	v_mfma_f32_16x16x32_bf16 v[70:73], v[158:161], v[218:221], v[70:73]
	v_mfma_f32_16x16x32_bf16 v[122:125], v[168:171], v[184:187], v[122:125]
	v_mfma_f32_16x16x32_bf16 v[114:117], v[176:179], v[184:187], v[114:117]
	v_mfma_f32_16x16x32_bf16 v[106:109], v[168:171], v[192:195], v[106:109]
	v_mfma_f32_16x16x32_bf16 v[98:101], v[176:179], v[192:195], v[98:101]
	v_mfma_f32_16x16x32_bf16 v[90:93], v[168:171], v[200:203], v[90:93]
	v_mfma_f32_16x16x32_bf16 v[82:85], v[176:179], v[200:203], v[82:85]
	v_mfma_f32_16x16x32_bf16 v[74:77], v[168:171], v[208:211], v[74:77]
	v_mfma_f32_16x16x32_bf16 v[66:69], v[176:179], v[208:211], v[66:69]
	v_mfma_f32_16x16x32_bf16 v[122:125], v[172:175], v[188:191], v[122:125]
	v_mfma_f32_16x16x32_bf16 v[114:117], v[180:183], v[188:191], v[114:117]
	v_mfma_f32_16x16x32_bf16 v[106:109], v[172:175], v[196:199], v[106:109]
	v_mfma_f32_16x16x32_bf16 v[98:101], v[180:183], v[196:199], v[98:101]
	v_mfma_f32_16x16x32_bf16 v[90:93], v[172:175], v[204:207], v[90:93]
	v_mfma_f32_16x16x32_bf16 v[82:85], v[180:183], v[204:207], v[82:85]
	v_mfma_f32_16x16x32_bf16 v[74:77], v[172:175], v[218:221], v[74:77]
	v_mfma_f32_16x16x32_bf16 v[66:69], v[180:183], v[218:221], v[66:69]
	s_setprio 0
	s_barrier
	s_add_i32 s55, s55, s36
	v_lshl_add_u64 v[162:163], s[28:29], 0, v[134:135]
	s_mov_b32 m0, s55
	ds_read_b128 v[184:187], v148 offset:16384
	ds_read_b128 v[188:191], v148 offset:17408
	ds_read_b128 v[192:195], v148 offset:18432
	ds_read_b128 v[196:199], v148 offset:19456
	ds_read_b128 v[200:203], v148 offset:20480
	ds_read_b128 v[204:207], v148 offset:21504
	ds_read_b128 v[208:211], v148 offset:22528
	ds_read_b128 v[218:221], v148 offset:23552
	global_load_lds_dwordx4 v[162:163], off
	s_add_i32 m0, s55, 0x2000
	s_add_u32 s58, s28, 0x80000
	v_lshl_add_u64 v[212:213], s[28:29], 0, v[130:131]
	s_addc_u32 s59, s29, 0
	s_add_i32 s55, s57, s36
	global_load_lds_dwordx4 v[212:213], off
	v_lshl_add_u64 v[226:227], s[58:59], 0, v[134:135]
	s_mov_b32 m0, s55
	v_lshl_add_u64 v[228:229], s[30:31], 0, v[132:133]
	global_load_lds_dwordx4 v[226:227], off
	v_lshl_add_u64 v[226:227], s[58:59], 0, v[130:131]
	s_add_i32 m0, s55, 0x2000
	s_nop 0
	global_load_lds_dwordx4 v[226:227], off
	v_lshl_add_u64 v[226:227], s[30:31], 0, v[136:137]
	s_mov_b32 m0, s37
	s_nop 0
	global_load_lds_dwordx4 v[226:227], off
	s_mov_b32 m0, s38
	s_nop 0
	global_load_lds_dwordx4 v[228:229], off
	s_waitcnt vmcnt(8)
	s_waitcnt lgkmcnt(0)
	s_barrier
; #define PG8_STAGE(bufoff, gbase, voff) do { _Pragma("unroll") for (int _i = 0; _i < 2; ++_i) \
;         __builtin_amdgcn_global_load_lds((const unsigned*)((const char*)(gbase) + (voff)[_i]), (PG8_LAS unsigned*)(lds + (bufoff) + ldsw + _i * 8192), 16, 0, 0); } while (0)
; #define PG8_LDA(dst, b, h) do { _Pragma("unroll") for (int m = 0; m < 4; ++m) _Pragma("unroll") for (int k = 0; k < 2; ++k) dst[m][k] = *(const PG8_LAS bf16x8*)(lds + PG8_SA(b, h) + aoff + m * 2048 + k * 1024); } while (0)
; #define PG8_LDB(dst, b, h) do { _Pragma("unroll") for (int n = 0; n < 2; ++n) _Pragma("unroll") for (int k = 0; k < 2; ++k) dst[n][k] = *(const PG8_LAS bf16x8*)(lds + PG8_SB(b, h) + boff + n * 2048 + k * 1024); } while (0)
; #define PG8_MMA(ai, bj, At, Bt) do { __builtin_amdgcn_s_setprio(1); _Pragma("unroll") for (int m = 0; m < 4; ++m) _Pragma("unroll") for (int n = 0; n < 2; ++n) _Pragma("unroll") for (int k = 0; k < 2; ++k) \
;         acc[ai][bj][m][n] = __builtin_amdgcn_mfma_f32_16x16x32_bf16(Bt[n][k], At[m][k], acc[ai][bj][m][n], 0, 0, 0); __builtin_amdgcn_s_setprio(0); } while (0)
; #define PG8_WAIT_V(n) asm volatile("s_waitcnt vmcnt(" #n ")" ::: "memory")
; #define PG8_WAIT_L(n) asm volatile("s_waitcnt lgkmcnt(" #n ")" ::: "memory")
; #define PG8_BAR __builtin_amdgcn_s_barrier()
; #define PG8_SCHED __builtin_amdgcn_sched_barrier(0)
; template <class Epi, class Sched, bool ALIGN_EPI = false, bool SP2 = false>
; __device__ __forceinline__ void gemm_phase(PG8_LAS unsigned char* lds, const Gemm g, const Sched& S, const Epi& E) {
;     ...
;             PG8_WAIT_V(8); PG8_WAIT_L(0); PG8_BAR; PG8_MMA(1, 0, At, B0); PG8_MMA(1, 1, At, B1); PG8_BAR; PG8_SCHED;
;             PG8_LDB(B0, 1, 0); PG8_LDB(B1, 1, 1); PG8_SCHED; PG8_LDA(At, 1, 0); PG8_STAGE(PG8_SA(0, 1), a2 + hstep, voffA);
;             PG8_WAIT_V(8); PG8_WAIT_L(0); PG8_BAR; PG8_MMA(0, 0, At, B0); PG8_MMA(0, 1, At, B1); PG8_BAR; PG8_SCHED;
	s_setprio 1
	s_waitcnt lgkmcnt(0)
	v_mfma_f32_16x16x32_bf16 v[62:65], v[142:145], v[184:187], v[62:65]
	v_mfma_f32_16x16x32_bf16 v[54:57], v[154:157], v[184:187], v[54:57]
	v_mfma_f32_16x16x32_bf16 v[46:49], v[142:145], v[192:195], v[46:49]
	v_mfma_f32_16x16x32_bf16 v[38:41], v[154:157], v[192:195], v[38:41]
	v_mfma_f32_16x16x32_bf16 v[30:33], v[142:145], v[200:203], v[30:33]
	v_mfma_f32_16x16x32_bf16 v[22:25], v[154:157], v[200:203], v[22:25]
	v_mfma_f32_16x16x32_bf16 v[14:17], v[142:145], v[208:211], v[14:17]
	v_mfma_f32_16x16x32_bf16 v[6:9], v[154:157], v[208:211], v[6:9]
	v_mfma_f32_16x16x32_bf16 v[62:65], v[150:153], v[188:191], v[62:65]
	v_mfma_f32_16x16x32_bf16 v[54:57], v[158:161], v[188:191], v[54:57]
	v_mfma_f32_16x16x32_bf16 v[46:49], v[150:153], v[196:199], v[46:49]
	v_mfma_f32_16x16x32_bf16 v[38:41], v[158:161], v[196:199], v[38:41]
	v_mfma_f32_16x16x32_bf16 v[30:33], v[150:153], v[204:207], v[30:33]
	v_mfma_f32_16x16x32_bf16 v[22:25], v[158:161], v[204:207], v[22:25]
	v_mfma_f32_16x16x32_bf16 v[14:17], v[150:153], v[218:221], v[14:17]
	v_mfma_f32_16x16x32_bf16 v[6:9], v[158:161], v[218:221], v[6:9]
	v_mfma_f32_16x16x32_bf16 v[58:61], v[168:171], v[184:187], v[58:61]
	v_mfma_f32_16x16x32_bf16 v[50:53], v[176:179], v[184:187], v[50:53]
	v_mfma_f32_16x16x32_bf16 v[42:45], v[168:171], v[192:195], v[42:45]
	v_mfma_f32_16x16x32_bf16 v[34:37], v[176:179], v[192:195], v[34:37]
	v_mfma_f32_16x16x32_bf16 v[26:29], v[168:171], v[200:203], v[26:29]
	v_mfma_f32_16x16x32_bf16 v[18:21], v[176:179], v[200:203], v[18:21]
	v_mfma_f32_16x16x32_bf16 v[10:13], v[168:171], v[208:211], v[10:13]
	v_mfma_f32_16x16x32_bf16 v[2:5], v[176:179], v[208:211], v[2:5]
	v_mfma_f32_16x16x32_bf16 v[58:61], v[172:175], v[188:191], v[58:61]
	v_mfma_f32_16x16x32_bf16 v[50:53], v[180:183], v[188:191], v[50:53]
	v_mfma_f32_16x16x32_bf16 v[42:45], v[172:175], v[196:199], v[42:45]
	v_mfma_f32_16x16x32_bf16 v[34:37], v[180:183], v[196:199], v[34:37]
	v_mfma_f32_16x16x32_bf16 v[26:29], v[172:175], v[204:207], v[26:29]
	v_mfma_f32_16x16x32_bf16 v[18:21], v[180:183], v[204:207], v[18:21]
	v_mfma_f32_16x16x32_bf16 v[10:13], v[172:175], v[218:221], v[10:13]
	v_mfma_f32_16x16x32_bf16 v[2:5], v[180:183], v[218:221], v[2:5]
	s_setprio 0
	s_barrier
	s_add_i32 s55, 0, 0x18000
	v_add_u32_e32 v149, s55, v146
	s_add_i32 s57, 0, 0x1c000
	ds_read_b128 v[142:145], v149
	ds_read_b128 v[150:153], v149 offset:1024
	ds_read_b128 v[154:157], v149 offset:2048
	ds_read_b128 v[158:161], v149 offset:3072
	v_add_u32_e32 v149, s57, v146
	ds_read_b128 v[168:171], v149
	ds_read_b128 v[172:175], v149 offset:1024
	ds_read_b128 v[176:179], v149 offset:2048
	ds_read_b128 v[180:183], v149 offset:3072
	s_add_u32 s30, s30, 0x80000
	s_addc_u32 s31, s31, 0
	s_mov_b32 m0, s39
	v_lshl_add_u64 v[230:231], s[30:31], 0, v[136:137]
	ds_read_b128 v[184:187], v148 offset:32768
	ds_read_b128 v[188:191], v148 offset:33792
	ds_read_b128 v[192:195], v148 offset:34816
	ds_read_b128 v[196:199], v148 offset:35840
	ds_read_b128 v[200:203], v148 offset:36864
	ds_read_b128 v[204:207], v148 offset:37888
	ds_read_b128 v[208:211], v148 offset:38912
	ds_read_b128 v[218:221], v148 offset:39936
	global_load_lds_dwordx4 v[230:231], off
	v_lshl_add_u64 v[230:231], s[30:31], 0, v[132:133]
	s_mov_b32 m0, s40
	s_nop 0
	global_load_lds_dwordx4 v[230:231], off
	s_waitcnt vmcnt(8)
	s_waitcnt lgkmcnt(0)
	s_barrier
	s_setprio 1
	s_waitcnt lgkmcnt(0)
	v_mfma_f32_16x16x32_bf16 v[126:129], v[142:145], v[184:187], v[126:129]
	v_mfma_f32_16x16x32_bf16 v[118:121], v[154:157], v[184:187], v[118:121]
	v_mfma_f32_16x16x32_bf16 v[110:113], v[142:145], v[192:195], v[110:113]
	v_mfma_f32_16x16x32_bf16 v[102:105], v[154:157], v[192:195], v[102:105]
	v_mfma_f32_16x16x32_bf16 v[94:97], v[142:145], v[200:203], v[94:97]
	v_mfma_f32_16x16x32_bf16 v[86:89], v[154:157], v[200:203], v[86:89]
	v_mfma_f32_16x16x32_bf16 v[78:81], v[142:145], v[208:211], v[78:81]
	v_mfma_f32_16x16x32_bf16 v[70:73], v[154:157], v[208:211], v[70:73]
	v_mfma_f32_16x16x32_bf16 v[126:129], v[150:153], v[188:191], v[126:129]
	v_mfma_f32_16x16x32_bf16 v[118:121], v[158:161], v[188:191], v[118:121]
	v_mfma_f32_16x16x32_bf16 v[110:113], v[150:153], v[196:199], v[110:113]
	v_mfma_f32_16x16x32_bf16 v[102:105], v[158:161], v[196:199], v[102:105]
	v_mfma_f32_16x16x32_bf16 v[94:97], v[150:153], v[204:207], v[94:97]
	v_mfma_f32_16x16x32_bf16 v[86:89], v[158:161], v[204:207], v[86:89]
	v_mfma_f32_16x16x32_bf16 v[78:81], v[150:153], v[218:221], v[78:81]
	v_mfma_f32_16x16x32_bf16 v[70:73], v[158:161], v[218:221], v[70:73]
	v_mfma_f32_16x16x32_bf16 v[122:125], v[168:171], v[184:187], v[122:125]
	v_mfma_f32_16x16x32_bf16 v[114:117], v[176:179], v[184:187], v[114:117]
	v_mfma_f32_16x16x32_bf16 v[106:109], v[168:171], v[192:195], v[106:109]
	v_mfma_f32_16x16x32_bf16 v[98:101], v[176:179], v[192:195], v[98:101]
	v_mfma_f32_16x16x32_bf16 v[90:93], v[168:171], v[200:203], v[90:93]
	v_mfma_f32_16x16x32_bf16 v[82:85], v[176:179], v[200:203], v[82:85]
	v_mfma_f32_16x16x32_bf16 v[74:77], v[168:171], v[208:211], v[74:77]
	v_mfma_f32_16x16x32_bf16 v[66:69], v[176:179], v[208:211], v[66:69]
	v_mfma_f32_16x16x32_bf16 v[122:125], v[172:175], v[188:191], v[122:125]
	v_mfma_f32_16x16x32_bf16 v[114:117], v[180:183], v[188:191], v[114:117]
	v_mfma_f32_16x16x32_bf16 v[106:109], v[172:175], v[196:199], v[106:109]
	v_mfma_f32_16x16x32_bf16 v[98:101], v[180:183], v[196:199], v[98:101]
	v_mfma_f32_16x16x32_bf16 v[90:93], v[172:175], v[204:207], v[90:93]
	v_mfma_f32_16x16x32_bf16 v[82:85], v[180:183], v[204:207], v[82:85]
	v_mfma_f32_16x16x32_bf16 v[74:77], v[172:175], v[218:221], v[74:77]
	v_mfma_f32_16x16x32_bf16 v[66:69], v[180:183], v[218:221], v[66:69]
	s_setprio 0
	s_barrier
; #define PG8_STAGE(bufoff, gbase, voff) do { _Pragma("unroll") for (int _i = 0; _i < 2; ++_i) \
;         __builtin_amdgcn_global_load_lds((const unsigned*)((const char*)(gbase) + (voff)[_i]), (PG8_LAS unsigned*)(lds + (bufoff) + ldsw + _i * 8192), 16, 0, 0); } while (0)
; #define PG8_LDA(dst, b, h) do { _Pragma("unroll") for (int m = 0; m < 4; ++m) _Pragma("unroll") for (int k = 0; k < 2; ++k) dst[m][k] = *(const PG8_LAS bf16x8*)(lds + PG8_SA(b, h) + aoff + m * 2048 + k * 1024); } while (0)
; #define PG8_MMA(ai, bj, At, Bt) do { __builtin_amdgcn_s_setprio(1); _Pragma("unroll") for (int m = 0; m < 4; ++m) _Pragma("unroll") for (int n = 0; n < 2; ++n) _Pragma("unroll") for (int k = 0; k < 2; ++k) \
;         acc[ai][bj][m][n] = __builtin_amdgcn_mfma_f32_16x16x32_bf16(Bt[n][k], At[m][k], acc[ai][bj][m][n], 0, 0, 0); __builtin_amdgcn_s_setprio(0); } while (0)
; #define PG8_WAIT_V(n) asm volatile("s_waitcnt vmcnt(" #n ")" ::: "memory")
; #define PG8_WAIT_L(n) asm volatile("s_waitcnt lgkmcnt(" #n ")" ::: "memory")
; #define PG8_BAR __builtin_amdgcn_s_barrier()
; #define PG8_SCHED __builtin_amdgcn_sched_barrier(0)
; template <class Epi, class Sched, bool ALIGN_EPI = false, bool SP2 = false>
; __device__ __forceinline__ void gemm_phase(PG8_LAS unsigned char* lds, const Gemm g, const Sched& S, const Epi& E) {
;     ...
;         for (int t = 0; t < nt; t += 2) {
;     ...
;             PG8_LDA(At, 1, 1); PG8_STAGE(PG8_SB(1, 0), b3, voffB); PG8_STAGE(PG8_SB(1, 1), b3 + hstep, voffB); PG8_STAGE(PG8_SA(1, 0), a3, voffA);
;             PG8_WAIT_V(8); PG8_WAIT_L(0); PG8_BAR; PG8_MMA(1, 0, At, B0); PG8_MMA(1, 1, At, B1); PG8_BAR; PG8_SCHED;
	s_add_i32 s30, s55, s36
	v_lshl_add_u64 v[162:163], v[162:163], 0, s[84:85]
	s_mov_b32 m0, s30
	ds_read_b128 v[184:187], v148 offset:49152
	ds_read_b128 v[188:191], v148 offset:50176
	ds_read_b128 v[192:195], v148 offset:51200
	ds_read_b128 v[196:199], v148 offset:52224
	ds_read_b128 v[200:203], v148 offset:53248
	ds_read_b128 v[204:207], v148 offset:54272
	ds_read_b128 v[208:211], v148 offset:55296
	ds_read_b128 v[218:221], v148 offset:56320
	global_load_lds_dwordx4 v[162:163], off
	s_add_i32 m0, s30, 0x2000
	s_add_u32 s28, s28, 0x80080
	v_lshl_add_u64 v[162:163], v[212:213], 0, s[84:85]
	s_addc_u32 s29, s29, 0
	s_add_i32 s30, s57, s36
	global_load_lds_dwordx4 v[162:163], off
	v_lshl_add_u64 v[162:163], s[28:29], 0, v[134:135]
	s_mov_b32 m0, s30
	s_nop 0
	global_load_lds_dwordx4 v[162:163], off
	v_lshl_add_u64 v[162:163], s[28:29], 0, v[130:131]
	s_add_i32 m0, s30, 0x2000
	s_nop 0
	global_load_lds_dwordx4 v[162:163], off
	v_lshl_add_u64 v[162:163], v[226:227], 0, s[84:85]
	s_mov_b32 m0, s41
	s_nop 0
	global_load_lds_dwordx4 v[162:163], off
	v_lshl_add_u64 v[162:163], v[228:229], 0, s[84:85]
	s_mov_b32 m0, s42
	s_nop 0
	global_load_lds_dwordx4 v[162:163], off
	s_waitcnt vmcnt(8)
	s_waitcnt lgkmcnt(0)
	s_barrier
	s_setprio 1
	s_waitcnt lgkmcnt(0)
	v_mfma_f32_16x16x32_bf16 v[62:65], v[142:145], v[184:187], v[62:65]
	v_mfma_f32_16x16x32_bf16 v[54:57], v[154:157], v[184:187], v[54:57]
	v_mfma_f32_16x16x32_bf16 v[46:49], v[142:145], v[192:195], v[46:49]
	v_mfma_f32_16x16x32_bf16 v[38:41], v[154:157], v[192:195], v[38:41]
	v_mfma_f32_16x16x32_bf16 v[30:33], v[142:145], v[200:203], v[30:33]
	v_mfma_f32_16x16x32_bf16 v[22:25], v[154:157], v[200:203], v[22:25]
	v_mfma_f32_16x16x32_bf16 v[14:17], v[142:145], v[208:211], v[14:17]
	v_mfma_f32_16x16x32_bf16 v[6:9], v[154:157], v[208:211], v[6:9]
	v_mfma_f32_16x16x32_bf16 v[62:65], v[150:153], v[188:191], v[62:65]
	v_mfma_f32_16x16x32_bf16 v[54:57], v[158:161], v[188:191], v[54:57]
	v_mfma_f32_16x16x32_bf16 v[46:49], v[150:153], v[196:199], v[46:49]
	v_mfma_f32_16x16x32_bf16 v[38:41], v[158:161], v[196:199], v[38:41]
	v_mfma_f32_16x16x32_bf16 v[30:33], v[150:153], v[204:207], v[30:33]
	v_mfma_f32_16x16x32_bf16 v[22:25], v[158:161], v[204:207], v[22:25]
	v_mfma_f32_16x16x32_bf16 v[14:17], v[150:153], v[218:221], v[14:17]
	v_mfma_f32_16x16x32_bf16 v[6:9], v[158:161], v[218:221], v[6:9]
	v_mfma_f32_16x16x32_bf16 v[58:61], v[168:171], v[184:187], v[58:61]
	v_mfma_f32_16x16x32_bf16 v[50:53], v[176:179], v[184:187], v[50:53]
	v_mfma_f32_16x16x32_bf16 v[42:45], v[168:171], v[192:195], v[42:45]
	v_mfma_f32_16x16x32_bf16 v[34:37], v[176:179], v[192:195], v[34:37]
	v_mfma_f32_16x16x32_bf16 v[26:29], v[168:171], v[200:203], v[26:29]
	v_mfma_f32_16x16x32_bf16 v[18:21], v[176:179], v[200:203], v[18:21]
	v_mfma_f32_16x16x32_bf16 v[10:13], v[168:171], v[208:211], v[10:13]
	v_mfma_f32_16x16x32_bf16 v[2:5], v[176:179], v[208:211], v[2:5]
	v_mfma_f32_16x16x32_bf16 v[58:61], v[172:175], v[188:191], v[58:61]
	v_mfma_f32_16x16x32_bf16 v[50:53], v[180:183], v[188:191], v[50:53]
	v_mfma_f32_16x16x32_bf16 v[42:45], v[172:175], v[196:199], v[42:45]
	v_mfma_f32_16x16x32_bf16 v[34:37], v[180:183], v[196:199], v[34:37]
	v_mfma_f32_16x16x32_bf16 v[26:29], v[172:175], v[204:207], v[26:29]
	v_mfma_f32_16x16x32_bf16 v[18:21], v[180:183], v[204:207], v[18:21]
	v_mfma_f32_16x16x32_bf16 v[10:13], v[172:175], v[218:221], v[10:13]
	v_mfma_f32_16x16x32_bf16 v[2:5], v[180:183], v[218:221], v[2:5]
	s_setprio 0
	s_barrier
	s_add_i32 s54, s54, 2
	s_add_u32 s26, s26, 0x100
	s_addc_u32 s27, s27, 0
	s_add_u32 s51, s51, 0x100
	s_addc_u32 s52, s52, 0
	s_cmp_gt_u32 s54, 29
	s_cbranch_scc0 .LBB0_133
	s_and_b64 vcc, exec, s[16:17]
	s_cbranch_vccz .LBB0_136
	s_barrier

; #define PG8_STAGE(bufoff, gbase, voff) do { _Pragma("unroll") for (int _i = 0; _i < 2; ++_i) \
;         __builtin_amdgcn_global_load_lds((const unsigned*)((const char*)(gbase) + (voff)[_i]), (PG8_LAS unsigned*)(lds + (bufoff) + ldsw + _i * 8192), 16, 0, 0); } while (0)
; #define PG8_LDA(dst, b, h) do { _Pragma("unroll") for (int m = 0; m < 4; ++m) _Pragma("unroll") for (int k = 0; k < 2; ++k) dst[m][k] = *(const PG8_LAS bf16x8*)(lds + PG8_SA(b, h) + aoff + m * 2048 + k * 1024); } while (0)
; #define PG8_LDB(dst, b, h) do { _Pragma("unroll") for (int n = 0; n < 2; ++n) _Pragma("unroll") for (int k = 0; k < 2; ++k) dst[n][k] = *(const PG8_LAS bf16x8*)(lds + PG8_SB(b, h) + boff + n * 2048 + k * 1024); } while (0)
; #define PG8_MMA(ai, bj, At, Bt) do { __builtin_amdgcn_s_setprio(1); _Pragma("unroll") for (int m = 0; m < 4; ++m) _Pragma("unroll") for (int n = 0; n < 2; ++n) _Pragma("unroll") for (int k = 0; k < 2; ++k) \
;         acc[ai][bj][m][n] = __builtin_amdgcn_mfma_f32_16x16x32_bf16(Bt[n][k], At[m][k], acc[ai][bj][m][n], 0, 0, 0); __builtin_amdgcn_s_setprio(0); } while (0)
; #define PG8_WAIT_V(n) asm volatile("s_waitcnt vmcnt(" #n ")" ::: "memory")
; #define PG8_WAIT_L(n) asm volatile("s_waitcnt lgkmcnt(" #n ")" ::: "memory")
; #define PG8_BAR __builtin_amdgcn_s_barrier()
; #define PG8_SCHED __builtin_amdgcn_sched_barrier(0)
; template <class Epi, class Sched, bool ALIGN_EPI = false, bool SP2 = false>
; __device__ __forceinline__ void gemm_phase(PG8_LAS unsigned char* lds, const Gemm g, const Sched& S, const Epi& E) {
;     ...
;             PG8_LDB(B0, 0, 0); PG8_LDB(B1, 0, 1); PG8_SCHED; PG8_LDA(At, 0, 0); PG8_STAGE(PG8_SA(1, 1), a1 + hstep, voffA);
;             PG8_WAIT_V(8); PG8_WAIT_L(0); PG8_BAR; PG8_MMA(0, 0, At, B0); PG8_MMA(0, 1, At, B1); PG8_BAR; PG8_SCHED;
;             PG8_LDA(At, 0, 1); PG8_STAGE(PG8_SB(0, 0), b2, voffB); PG8_STAGE(PG8_SB(0, 1), b2 + hstep, voffB); PG8_STAGE(PG8_SA(0, 0), a2, voffA);
;             PG8_WAIT_V(8); PG8_WAIT_L(0); PG8_BAR; PG8_MMA(1, 0, At, B0); PG8_MMA(1, 1, At, B1); PG8_BAR; PG8_SCHED;
.LBB0_179:
	s_add_i32 s52, s26, 2
	s_add_u32 s54, s24, 0x80
	s_addc_u32 s27, s25, 0
	s_add_i32 s57, 0, 0x10000
	s_cmp_eq_u32 s42, s26
	s_cselect_b32 s27, s9, s27
	s_cselect_b32 s26, s8, s54
	s_cselect_b32 s55, s23, s51
	s_cselect_b32 s54, s22, s47
	s_add_i32 s58, 0, 0x14000
	v_add_u32_e32 v134, s57, v167
	v_add_u32_e32 v162, s58, v167
	ds_read_b128 v[106:109], v134
	ds_read_b128 v[110:113], v134 offset:1024
	ds_read_b128 v[130:133], v134 offset:2048
	ds_read_b128 v[134:137], v134 offset:3072
	ds_read_b128 v[158:161], v162
	ds_read_b128 v[170:173], v162 offset:1024
	ds_read_b128 v[174:177], v162 offset:2048
	ds_read_b128 v[178:181], v162 offset:3072
	v_lshl_add_u64 v[162:163], s[24:25], 0, v[154:155]
	s_add_i32 m0, s30, 0xc000
	ds_read_b128 v[182:185], v169
	ds_read_b128 v[186:189], v169 offset:1024
	ds_read_b128 v[190:193], v169 offset:2048
	ds_read_b128 v[194:197], v169 offset:3072
	ds_read_b128 v[198:201], v169 offset:4096
	ds_read_b128 v[202:205], v169 offset:5120
	ds_read_b128 v[206:209], v169 offset:6144
	ds_read_b128 v[210:213], v169 offset:7168
	global_load_lds_dwordx4 v[162:163], off
	v_lshl_add_u64 v[162:163], s[24:25], 0, v[156:157]
	s_add_i32 m0, s30, 0xe000
	s_nop 0
	global_load_lds_dwordx4 v[162:163], off
	s_waitcnt vmcnt(8)
	s_waitcnt lgkmcnt(0)
	s_barrier
	s_setprio 1
	s_waitcnt lgkmcnt(0)
	v_mfma_f32_16x16x32_bf16 v[142:145], v[106:109], v[182:185], v[142:145]
	v_mfma_f32_16x16x32_bf16 v[138:141], v[130:133], v[182:185], v[138:141]
	v_mfma_f32_16x16x32_bf16 v[118:121], v[106:109], v[190:193], v[118:121]
	v_mfma_f32_16x16x32_bf16 v[114:117], v[130:133], v[190:193], v[114:117]
	v_mfma_f32_16x16x32_bf16 v[94:97], v[106:109], v[198:201], v[94:97]
	v_mfma_f32_16x16x32_bf16 v[90:93], v[130:133], v[198:201], v[90:93]
	v_mfma_f32_16x16x32_bf16 v[78:81], v[106:109], v[206:209], v[78:81]
	v_mfma_f32_16x16x32_bf16 v[74:77], v[130:133], v[206:209], v[74:77]
	v_mfma_f32_16x16x32_bf16 v[142:145], v[110:113], v[186:189], v[142:145]
	v_mfma_f32_16x16x32_bf16 v[138:141], v[134:137], v[186:189], v[138:141]
	v_mfma_f32_16x16x32_bf16 v[118:121], v[110:113], v[194:197], v[118:121]
	v_mfma_f32_16x16x32_bf16 v[114:117], v[134:137], v[194:197], v[114:117]
	v_mfma_f32_16x16x32_bf16 v[94:97], v[110:113], v[202:205], v[94:97]
	v_mfma_f32_16x16x32_bf16 v[90:93], v[134:137], v[202:205], v[90:93]
	v_mfma_f32_16x16x32_bf16 v[78:81], v[110:113], v[210:213], v[78:81]
	v_mfma_f32_16x16x32_bf16 v[74:77], v[134:137], v[210:213], v[74:77]
	v_mfma_f32_16x16x32_bf16 v[126:129], v[158:161], v[182:185], v[126:129]
	v_mfma_f32_16x16x32_bf16 v[122:125], v[174:177], v[182:185], v[122:125]
	v_mfma_f32_16x16x32_bf16 v[102:105], v[158:161], v[190:193], v[102:105]
	v_mfma_f32_16x16x32_bf16 v[98:101], v[174:177], v[190:193], v[98:101]
	v_mfma_f32_16x16x32_bf16 v[86:89], v[158:161], v[198:201], v[86:89]
	v_mfma_f32_16x16x32_bf16 v[82:85], v[174:177], v[198:201], v[82:85]
	v_mfma_f32_16x16x32_bf16 v[70:73], v[158:161], v[206:209], v[70:73]
	v_mfma_f32_16x16x32_bf16 v[66:69], v[174:177], v[206:209], v[66:69]
	v_mfma_f32_16x16x32_bf16 v[126:129], v[170:173], v[186:189], v[126:129]
	v_mfma_f32_16x16x32_bf16 v[122:125], v[178:181], v[186:189], v[122:125]
	v_mfma_f32_16x16x32_bf16 v[102:105], v[170:173], v[194:197], v[102:105]
	v_mfma_f32_16x16x32_bf16 v[98:101], v[178:181], v[194:197], v[98:101]
	v_mfma_f32_16x16x32_bf16 v[86:89], v[170:173], v[202:205], v[86:89]
	v_mfma_f32_16x16x32_bf16 v[82:85], v[178:181], v[202:205], v[82:85]
	v_mfma_f32_16x16x32_bf16 v[70:73], v[170:173], v[210:213], v[70:73]
	v_mfma_f32_16x16x32_bf16 v[66:69], v[178:181], v[210:213], v[66:69]
	s_setprio 0
	s_barrier
	s_add_i32 s57, s57, s29
	v_lshl_add_u64 v[162:163], s[54:55], 0, v[150:151]
	s_mov_b32 m0, s57
	ds_read_b128 v[182:185], v169 offset:16384
	ds_read_b128 v[186:189], v169 offset:17408
	ds_read_b128 v[190:193], v169 offset:18432
	ds_read_b128 v[194:197], v169 offset:19456
	ds_read_b128 v[198:201], v169 offset:20480
	ds_read_b128 v[202:205], v169 offset:21504
	ds_read_b128 v[206:209], v169 offset:22528
	ds_read_b128 v[210:213], v169 offset:23552
	global_load_lds_dwordx4 v[162:163], off
	s_add_i32 m0, s57, 0x2000
	v_lshl_add_u64 v[218:219], s[54:55], 0, v[146:147]
	s_add_u32 s54, s54, s90
	s_addc_u32 s55, s55, 0
	s_add_i32 s57, s58, s29
	global_load_lds_dwordx4 v[218:219], off
	v_lshl_add_u64 v[220:221], s[54:55], 0, v[150:151]
	s_mov_b32 m0, s57
	v_lshl_add_u64 v[226:227], s[54:55], 0, v[146:147]
	global_load_lds_dwordx4 v[220:221], off
	s_add_i32 m0, s57, 0x2000
	v_lshl_add_u64 v[228:229], s[26:27], 0, v[152:153]
	global_load_lds_dwordx4 v[226:227], off
	s_mov_b32 m0, s30
	v_lshl_add_u64 v[230:231], s[26:27], 0, v[148:149]
	global_load_lds_dwordx4 v[228:229], off
	s_mov_b32 m0, s31
	s_nop 0
	global_load_lds_dwordx4 v[230:231], off
	s_waitcnt vmcnt(8)
	s_waitcnt lgkmcnt(0)
	s_barrier
; #define PG8_STAGE(bufoff, gbase, voff) do { _Pragma("unroll") for (int _i = 0; _i < 2; ++_i) \
;         __builtin_amdgcn_global_load_lds((const unsigned*)((const char*)(gbase) + (voff)[_i]), (PG8_LAS unsigned*)(lds + (bufoff) + ldsw + _i * 8192), 16, 0, 0); } while (0)
; #define PG8_LDA(dst, b, h) do { _Pragma("unroll") for (int m = 0; m < 4; ++m) _Pragma("unroll") for (int k = 0; k < 2; ++k) dst[m][k] = *(const PG8_LAS bf16x8*)(lds + PG8_SA(b, h) + aoff + m * 2048 + k * 1024); } while (0)
; #define PG8_LDB(dst, b, h) do { _Pragma("unroll") for (int n = 0; n < 2; ++n) _Pragma("unroll") for (int k = 0; k < 2; ++k) dst[n][k] = *(const PG8_LAS bf16x8*)(lds + PG8_SB(b, h) + boff + n * 2048 + k * 1024); } while (0)
; #define PG8_MMA(ai, bj, At, Bt) do { __builtin_amdgcn_s_setprio(1); _Pragma("unroll") for (int m = 0; m < 4; ++m) _Pragma("unroll") for (int n = 0; n < 2; ++n) _Pragma("unroll") for (int k = 0; k < 2; ++k) \
;         acc[ai][bj][m][n] = __builtin_amdgcn_mfma_f32_16x16x32_bf16(Bt[n][k], At[m][k], acc[ai][bj][m][n], 0, 0, 0); __builtin_amdgcn_s_setprio(0); } while (0)
; #define PG8_WAIT_V(n) asm volatile("s_waitcnt vmcnt(" #n ")" ::: "memory")
; #define PG8_WAIT_L(n) asm volatile("s_waitcnt lgkmcnt(" #n ")" ::: "memory")
; #define PG8_BAR __builtin_amdgcn_s_barrier()
; #define PG8_SCHED __builtin_amdgcn_sched_barrier(0)
; template <class Epi, class Sched, bool ALIGN_EPI = false, bool SP2 = false>
; __device__ __forceinline__ void gemm_phase(PG8_LAS unsigned char* lds, const Gemm g, const Sched& S, const Epi& E) {
;     ...
;             PG8_WAIT_V(8); PG8_WAIT_L(0); PG8_BAR; PG8_MMA(1, 0, At, B0); PG8_MMA(1, 1, At, B1); PG8_BAR; PG8_SCHED;
;             PG8_LDB(B0, 1, 0); PG8_LDB(B1, 1, 1); PG8_SCHED; PG8_LDA(At, 1, 0); PG8_STAGE(PG8_SA(0, 1), a2 + hstep, voffA);
;             PG8_WAIT_V(8); PG8_WAIT_L(0); PG8_BAR; PG8_MMA(0, 0, At, B0); PG8_MMA(0, 1, At, B1); PG8_BAR; PG8_SCHED;
	s_setprio 1
	s_waitcnt lgkmcnt(0)
	v_mfma_f32_16x16x32_bf16 v[62:65], v[106:109], v[182:185], v[62:65]
	v_mfma_f32_16x16x32_bf16 v[58:61], v[130:133], v[182:185], v[58:61]
	v_mfma_f32_16x16x32_bf16 v[46:49], v[106:109], v[190:193], v[46:49]
	v_mfma_f32_16x16x32_bf16 v[42:45], v[130:133], v[190:193], v[42:45]
	v_mfma_f32_16x16x32_bf16 v[30:33], v[106:109], v[198:201], v[30:33]
	v_mfma_f32_16x16x32_bf16 v[26:29], v[130:133], v[198:201], v[26:29]
	v_mfma_f32_16x16x32_bf16 v[14:17], v[106:109], v[206:209], v[14:17]
	v_mfma_f32_16x16x32_bf16 v[10:13], v[130:133], v[206:209], v[10:13]
	v_mfma_f32_16x16x32_bf16 v[62:65], v[110:113], v[186:189], v[62:65]
	v_mfma_f32_16x16x32_bf16 v[58:61], v[134:137], v[186:189], v[58:61]
	v_mfma_f32_16x16x32_bf16 v[46:49], v[110:113], v[194:197], v[46:49]
	v_mfma_f32_16x16x32_bf16 v[42:45], v[134:137], v[194:197], v[42:45]
	v_mfma_f32_16x16x32_bf16 v[30:33], v[110:113], v[202:205], v[30:33]
	v_mfma_f32_16x16x32_bf16 v[26:29], v[134:137], v[202:205], v[26:29]
	v_mfma_f32_16x16x32_bf16 v[14:17], v[110:113], v[210:213], v[14:17]
	v_mfma_f32_16x16x32_bf16 v[10:13], v[134:137], v[210:213], v[10:13]
	v_mfma_f32_16x16x32_bf16 v[54:57], v[158:161], v[182:185], v[54:57]
	v_mfma_f32_16x16x32_bf16 v[50:53], v[174:177], v[182:185], v[50:53]
	v_mfma_f32_16x16x32_bf16 v[38:41], v[158:161], v[190:193], v[38:41]
	v_mfma_f32_16x16x32_bf16 v[34:37], v[174:177], v[190:193], v[34:37]
	v_mfma_f32_16x16x32_bf16 v[22:25], v[158:161], v[198:201], v[22:25]
	v_mfma_f32_16x16x32_bf16 v[18:21], v[174:177], v[198:201], v[18:21]
	v_mfma_f32_16x16x32_bf16 v[6:9], v[158:161], v[206:209], v[6:9]
	v_mfma_f32_16x16x32_bf16 v[2:5], v[174:177], v[206:209], v[2:5]
	v_mfma_f32_16x16x32_bf16 v[54:57], v[170:173], v[186:189], v[54:57]
	v_mfma_f32_16x16x32_bf16 v[50:53], v[178:181], v[186:189], v[50:53]
	v_mfma_f32_16x16x32_bf16 v[38:41], v[170:173], v[194:197], v[38:41]
	v_mfma_f32_16x16x32_bf16 v[34:37], v[178:181], v[194:197], v[34:37]
	v_mfma_f32_16x16x32_bf16 v[22:25], v[170:173], v[202:205], v[22:25]
	v_mfma_f32_16x16x32_bf16 v[18:21], v[178:181], v[202:205], v[18:21]
	v_mfma_f32_16x16x32_bf16 v[6:9], v[170:173], v[210:213], v[6:9]
	v_mfma_f32_16x16x32_bf16 v[2:5], v[178:181], v[210:213], v[2:5]
	s_setprio 0
	s_barrier
	s_add_i32 s54, 0, 0x18000
	s_add_i32 s55, 0, 0x1c000
	v_add_u32_e32 v134, s54, v167
	v_add_u32_e32 v178, s55, v167
	ds_read_b128 v[106:109], v134
	ds_read_b128 v[110:113], v134 offset:1024
	ds_read_b128 v[130:133], v134 offset:2048
	ds_read_b128 v[134:137], v134 offset:3072
	ds_read_b128 v[158:161], v178
	ds_read_b128 v[170:173], v178 offset:1024
	ds_read_b128 v[174:177], v178 offset:2048
	ds_read_b128 v[178:181], v178 offset:3072
	s_add_u32 s26, s26, s90
	s_addc_u32 s27, s27, 0
	s_mov_b32 m0, s34
	v_lshl_add_u64 v[232:233], s[26:27], 0, v[152:153]
	ds_read_b128 v[182:185], v169 offset:32768
	ds_read_b128 v[186:189], v169 offset:33792
	ds_read_b128 v[190:193], v169 offset:34816
	ds_read_b128 v[194:197], v169 offset:35840
	ds_read_b128 v[198:201], v169 offset:36864
	ds_read_b128 v[202:205], v169 offset:37888
	ds_read_b128 v[206:209], v169 offset:38912
	ds_read_b128 v[210:213], v169 offset:39936
	global_load_lds_dwordx4 v[232:233], off
	v_lshl_add_u64 v[232:233], s[26:27], 0, v[148:149]
	s_mov_b32 m0, s35
	s_nop 0
	global_load_lds_dwordx4 v[232:233], off
	s_waitcnt vmcnt(8)
	s_waitcnt lgkmcnt(0)
	s_barrier
	s_setprio 1
	s_waitcnt lgkmcnt(0)
	v_mfma_f32_16x16x32_bf16 v[142:145], v[106:109], v[182:185], v[142:145]
	v_mfma_f32_16x16x32_bf16 v[138:141], v[130:133], v[182:185], v[138:141]
	v_mfma_f32_16x16x32_bf16 v[118:121], v[106:109], v[190:193], v[118:121]
	v_mfma_f32_16x16x32_bf16 v[114:117], v[130:133], v[190:193], v[114:117]
	v_mfma_f32_16x16x32_bf16 v[94:97], v[106:109], v[198:201], v[94:97]
	v_mfma_f32_16x16x32_bf16 v[90:93], v[130:133], v[198:201], v[90:93]
	v_mfma_f32_16x16x32_bf16 v[78:81], v[106:109], v[206:209], v[78:81]
	v_mfma_f32_16x16x32_bf16 v[74:77], v[130:133], v[206:209], v[74:77]
	v_mfma_f32_16x16x32_bf16 v[142:145], v[110:113], v[186:189], v[142:145]
	v_mfma_f32_16x16x32_bf16 v[138:141], v[134:137], v[186:189], v[138:141]
	v_mfma_f32_16x16x32_bf16 v[118:121], v[110:113], v[194:197], v[118:121]
	v_mfma_f32_16x16x32_bf16 v[114:117], v[134:137], v[194:197], v[114:117]
	v_mfma_f32_16x16x32_bf16 v[94:97], v[110:113], v[202:205], v[94:97]
	v_mfma_f32_16x16x32_bf16 v[90:93], v[134:137], v[202:205], v[90:93]
	v_mfma_f32_16x16x32_bf16 v[78:81], v[110:113], v[210:213], v[78:81]
	v_mfma_f32_16x16x32_bf16 v[74:77], v[134:137], v[210:213], v[74:77]
	v_mfma_f32_16x16x32_bf16 v[126:129], v[158:161], v[182:185], v[126:129]
	v_mfma_f32_16x16x32_bf16 v[122:125], v[174:177], v[182:185], v[122:125]
	v_mfma_f32_16x16x32_bf16 v[102:105], v[158:161], v[190:193], v[102:105]
	v_mfma_f32_16x16x32_bf16 v[98:101], v[174:177], v[190:193], v[98:101]
	v_mfma_f32_16x16x32_bf16 v[86:89], v[158:161], v[198:201], v[86:89]
	v_mfma_f32_16x16x32_bf16 v[82:85], v[174:177], v[198:201], v[82:85]
	v_mfma_f32_16x16x32_bf16 v[70:73], v[158:161], v[206:209], v[70:73]
	v_mfma_f32_16x16x32_bf16 v[66:69], v[174:177], v[206:209], v[66:69]
	v_mfma_f32_16x16x32_bf16 v[126:129], v[170:173], v[186:189], v[126:129]
	v_mfma_f32_16x16x32_bf16 v[122:125], v[178:181], v[186:189], v[122:125]
	v_mfma_f32_16x16x32_bf16 v[102:105], v[170:173], v[194:197], v[102:105]
	v_mfma_f32_16x16x32_bf16 v[98:101], v[178:181], v[194:197], v[98:101]
	v_mfma_f32_16x16x32_bf16 v[86:89], v[170:173], v[202:205], v[86:89]
	v_mfma_f32_16x16x32_bf16 v[82:85], v[178:181], v[202:205], v[82:85]
	v_mfma_f32_16x16x32_bf16 v[70:73], v[170:173], v[210:213], v[70:73]
	v_mfma_f32_16x16x32_bf16 v[66:69], v[178:181], v[210:213], v[66:69]
	s_setprio 0
	s_barrier
; #define PG8_STAGE(bufoff, gbase, voff) do { _Pragma("unroll") for (int _i = 0; _i < 2; ++_i) \
;         __builtin_amdgcn_global_load_lds((const unsigned*)((const char*)(gbase) + (voff)[_i]), (PG8_LAS unsigned*)(lds + (bufoff) + ldsw + _i * 8192), 16, 0, 0); } while (0)
; #define PG8_LDA(dst, b, h) do { _Pragma("unroll") for (int m = 0; m < 4; ++m) _Pragma("unroll") for (int k = 0; k < 2; ++k) dst[m][k] = *(const PG8_LAS bf16x8*)(lds + PG8_SA(b, h) + aoff + m * 2048 + k * 1024); } while (0)
; #define PG8_MMA(ai, bj, At, Bt) do { __builtin_amdgcn_s_setprio(1); _Pragma("unroll") for (int m = 0; m < 4; ++m) _Pragma("unroll") for (int n = 0; n < 2; ++n) _Pragma("unroll") for (int k = 0; k < 2; ++k) \
;         acc[ai][bj][m][n] = __builtin_amdgcn_mfma_f32_16x16x32_bf16(Bt[n][k], At[m][k], acc[ai][bj][m][n], 0, 0, 0); __builtin_amdgcn_s_setprio(0); } while (0)
; #define PG8_WAIT_V(n) asm volatile("s_waitcnt vmcnt(" #n ")" ::: "memory")
; #define PG8_WAIT_L(n) asm volatile("s_waitcnt lgkmcnt(" #n ")" ::: "memory")
; #define PG8_BAR __builtin_amdgcn_s_barrier()
; #define PG8_SCHED __builtin_amdgcn_sched_barrier(0)
; template <class Epi, class Sched, bool ALIGN_EPI = false, bool SP2 = false>
; __device__ __forceinline__ void gemm_phase(PG8_LAS unsigned char* lds, const Gemm g, const Sched& S, const Epi& E) {
;     ...
;         for (int t = 0; t < nt; t += 2) {
;     ...
;             PG8_LDA(At, 1, 1); PG8_STAGE(PG8_SB(1, 0), b3, voffB); PG8_STAGE(PG8_SB(1, 1), b3 + hstep, voffB); PG8_STAGE(PG8_SA(1, 0), a3, voffA);
;             PG8_WAIT_V(8); PG8_WAIT_L(0); PG8_BAR; PG8_MMA(1, 0, At, B0); PG8_MMA(1, 1, At, B1); PG8_BAR; PG8_SCHED;
	s_add_i32 s26, s54, s29
	v_lshl_add_u64 v[162:163], v[162:163], 0, s[84:85]
	s_mov_b32 m0, s26
	ds_read_b128 v[182:185], v169 offset:49152
	ds_read_b128 v[186:189], v169 offset:50176
	ds_read_b128 v[190:193], v169 offset:51200
	ds_read_b128 v[194:197], v169 offset:52224
	ds_read_b128 v[198:201], v169 offset:53248
	ds_read_b128 v[202:205], v169 offset:54272
	ds_read_b128 v[206:209], v169 offset:55296
	ds_read_b128 v[210:213], v169 offset:56320
	global_load_lds_dwordx4 v[162:163], off
	v_lshl_add_u64 v[162:163], v[218:219], 0, s[84:85]
	s_add_i32 m0, s26, 0x2000
	s_add_i32 s26, s55, s29
	global_load_lds_dwordx4 v[162:163], off
	v_lshl_add_u64 v[162:163], v[220:221], 0, s[84:85]
	s_mov_b32 m0, s26
	s_nop 0
	global_load_lds_dwordx4 v[162:163], off
	v_lshl_add_u64 v[162:163], v[226:227], 0, s[84:85]
	s_add_i32 m0, s26, 0x2000
	s_nop 0
	global_load_lds_dwordx4 v[162:163], off
	v_lshl_add_u64 v[162:163], v[228:229], 0, s[84:85]
	s_mov_b32 m0, s40
	s_nop 0
	global_load_lds_dwordx4 v[162:163], off
	v_lshl_add_u64 v[162:163], v[230:231], 0, s[84:85]
	s_mov_b32 m0, s41
	s_nop 0
	global_load_lds_dwordx4 v[162:163], off
	s_waitcnt vmcnt(8)
	s_waitcnt lgkmcnt(0)
	s_barrier
	s_setprio 1
	s_waitcnt lgkmcnt(0)
	v_mfma_f32_16x16x32_bf16 v[62:65], v[106:109], v[182:185], v[62:65]
	v_mfma_f32_16x16x32_bf16 v[58:61], v[130:133], v[182:185], v[58:61]
	v_mfma_f32_16x16x32_bf16 v[46:49], v[106:109], v[190:193], v[46:49]
	v_mfma_f32_16x16x32_bf16 v[42:45], v[130:133], v[190:193], v[42:45]
	v_mfma_f32_16x16x32_bf16 v[30:33], v[106:109], v[198:201], v[30:33]
	v_mfma_f32_16x16x32_bf16 v[26:29], v[130:133], v[198:201], v[26:29]
	v_mfma_f32_16x16x32_bf16 v[14:17], v[106:109], v[206:209], v[14:17]
	v_mfma_f32_16x16x32_bf16 v[10:13], v[130:133], v[206:209], v[10:13]
	v_mfma_f32_16x16x32_bf16 v[62:65], v[110:113], v[186:189], v[62:65]
	v_mfma_f32_16x16x32_bf16 v[58:61], v[134:137], v[186:189], v[58:61]
	v_mfma_f32_16x16x32_bf16 v[46:49], v[110:113], v[194:197], v[46:49]
	v_mfma_f32_16x16x32_bf16 v[42:45], v[134:137], v[194:197], v[42:45]
	v_mfma_f32_16x16x32_bf16 v[30:33], v[110:113], v[202:205], v[30:33]
	v_mfma_f32_16x16x32_bf16 v[26:29], v[134:137], v[202:205], v[26:29]
	v_mfma_f32_16x16x32_bf16 v[14:17], v[110:113], v[210:213], v[14:17]
	v_mfma_f32_16x16x32_bf16 v[10:13], v[134:137], v[210:213], v[10:13]
	v_mfma_f32_16x16x32_bf16 v[54:57], v[158:161], v[182:185], v[54:57]
	v_mfma_f32_16x16x32_bf16 v[50:53], v[174:177], v[182:185], v[50:53]
	v_mfma_f32_16x16x32_bf16 v[38:41], v[158:161], v[190:193], v[38:41]
	v_mfma_f32_16x16x32_bf16 v[34:37], v[174:177], v[190:193], v[34:37]
	v_mfma_f32_16x16x32_bf16 v[22:25], v[158:161], v[198:201], v[22:25]
	v_mfma_f32_16x16x32_bf16 v[18:21], v[174:177], v[198:201], v[18:21]
	v_mfma_f32_16x16x32_bf16 v[6:9], v[158:161], v[206:209], v[6:9]
	v_mfma_f32_16x16x32_bf16 v[2:5], v[174:177], v[206:209], v[2:5]
	v_mfma_f32_16x16x32_bf16 v[54:57], v[170:173], v[186:189], v[54:57]
	v_mfma_f32_16x16x32_bf16 v[50:53], v[178:181], v[186:189], v[50:53]
	v_mfma_f32_16x16x32_bf16 v[38:41], v[170:173], v[194:197], v[38:41]
	v_mfma_f32_16x16x32_bf16 v[34:37], v[178:181], v[194:197], v[34:37]
	v_mfma_f32_16x16x32_bf16 v[22:25], v[170:173], v[202:205], v[22:25]
	v_mfma_f32_16x16x32_bf16 v[18:21], v[178:181], v[202:205], v[18:21]
	v_mfma_f32_16x16x32_bf16 v[6:9], v[170:173], v[210:213], v[6:9]
	v_mfma_f32_16x16x32_bf16 v[2:5], v[178:181], v[210:213], v[2:5]
	s_setprio 0
	s_barrier
	s_add_u32 s24, s24, 0x100
	s_addc_u32 s25, s25, 0
	s_add_u32 s47, s47, 0x100
	s_addc_u32 s51, s51, 0
	s_cmp_ge_u32 s52, s39
	s_mov_b32 s26, s52
	s_cbranch_scc0 .LBB0_179
	s_and_b64 vcc, exec, s[20:21]
	s_cbranch_vccz .LBB0_182
	s_barrier

; #define PG8_STAGE(bufoff, gbase, voff) do { _Pragma("unroll") for (int _i = 0; _i < 2; ++_i) \
;         __builtin_amdgcn_global_load_lds((const unsigned*)((const char*)(gbase) + (voff)[_i]), (PG8_LAS unsigned*)(lds + (bufoff) + ldsw + _i * 8192), 16, 0, 0); } while (0)
; #define PG8_LDA(dst, b, h) do { _Pragma("unroll") for (int m = 0; m < 4; ++m) _Pragma("unroll") for (int k = 0; k < 2; ++k) dst[m][k] = *(const PG8_LAS bf16x8*)(lds + PG8_SA(b, h) + aoff + m * 2048 + k * 1024); } while (0)
; #define PG8_LDB(dst, b, h) do { _Pragma("unroll") for (int n = 0; n < 2; ++n) _Pragma("unroll") for (int k = 0; k < 2; ++k) dst[n][k] = *(const PG8_LAS bf16x8*)(lds + PG8_SB(b, h) + boff + n * 2048 + k * 1024); } while (0)
; #define PG8_MMA(ai, bj, At, Bt) do { __builtin_amdgcn_s_setprio(1); _Pragma("unroll") for (int m = 0; m < 4; ++m) _Pragma("unroll") for (int n = 0; n < 2; ++n) _Pragma("unroll") for (int k = 0; k < 2; ++k) \
;         acc[ai][bj][m][n] = __builtin_amdgcn_mfma_f32_16x16x32_bf16(Bt[n][k], At[m][k], acc[ai][bj][m][n], 0, 0, 0); __builtin_amdgcn_s_setprio(0); } while (0)
; #define PG8_WAIT_V(n) asm volatile("s_waitcnt vmcnt(" #n ")" ::: "memory")
; #define PG8_WAIT_L(n) asm volatile("s_waitcnt lgkmcnt(" #n ")" ::: "memory")
; #define PG8_BAR __builtin_amdgcn_s_barrier()
; #define PG8_SCHED __builtin_amdgcn_sched_barrier(0)
; template <class Epi, class Sched, bool ALIGN_EPI = false, bool SP2 = false>
; __device__ __forceinline__ void gemm_phase(PG8_LAS unsigned char* lds, const Gemm g, const Sched& S, const Epi& E) {
;     ...
;             PG8_LDB(B0, 0, 0); PG8_LDB(B1, 0, 1); PG8_SCHED; PG8_LDA(At, 0, 0); PG8_STAGE(PG8_SA(1, 1), a1 + hstep, voffA);
;             PG8_WAIT_V(8); PG8_WAIT_L(0); PG8_BAR; PG8_MMA(0, 0, At, B0); PG8_MMA(0, 1, At, B1); PG8_BAR; PG8_SCHED;
;             PG8_LDA(At, 0, 1); PG8_STAGE(PG8_SB(0, 0), b2, voffB); PG8_STAGE(PG8_SB(0, 1), b2 + hstep, voffB); PG8_STAGE(PG8_SA(0, 0), a2, voffA);
;             PG8_WAIT_V(8); PG8_WAIT_L(0); PG8_BAR; PG8_MMA(1, 0, At, B0); PG8_MMA(1, 1, At, B1); PG8_BAR; PG8_SCHED;
.LBB0_268:
	s_add_u32 s24, s6, 0xfff80080
	s_addc_u32 s25, s7, -1
	s_add_i32 s54, 0, 0x10000
	s_cmp_eq_u32 s52, 28
	s_cselect_b32 s27, s17, s25
	s_cselect_b32 s26, s29, s24
	v_add_u32_e32 v143, s54, v146
	s_cselect_b32 s25, s15, s51
	s_cselect_b32 s24, s46, s47
	s_add_i32 s57, 0, 0x14000
	ds_read_b128 v[148:151], v143
	ds_read_b128 v[152:155], v143 offset:1024
	ds_read_b128 v[156:159], v143 offset:2048
	ds_read_b128 v[160:163], v143 offset:3072
	v_add_u32_e32 v143, s57, v146
	ds_read_b128 v[166:169], v143
	ds_read_b128 v[170:173], v143 offset:1024
	ds_read_b128 v[174:177], v143 offset:2048
	ds_read_b128 v[178:181], v143 offset:3072
	v_lshl_add_u64 v[144:145], s[6:7], 0, v[138:139]
	s_add_i32 m0, s35, 0xc000
	ds_read_b128 v[182:185], v147
	ds_read_b128 v[186:189], v147 offset:1024
	ds_read_b128 v[190:193], v147 offset:2048
	ds_read_b128 v[194:197], v147 offset:3072
	ds_read_b128 v[198:201], v147 offset:4096
	ds_read_b128 v[202:205], v147 offset:5120
	ds_read_b128 v[206:209], v147 offset:6144
	ds_read_b128 v[210:213], v147 offset:7168
	global_load_lds_dwordx4 v[144:145], off
	v_lshl_add_u64 v[144:145], s[6:7], 0, v[140:141]
	s_add_i32 m0, s35, 0xe000
	s_nop 0
	global_load_lds_dwordx4 v[144:145], off
	s_waitcnt vmcnt(8)
	s_waitcnt lgkmcnt(0)
	s_barrier
	s_setprio 1
	s_waitcnt lgkmcnt(0)
	v_mfma_f32_16x16x32_bf16 v[126:129], v[148:151], v[182:185], v[126:129]
	v_mfma_f32_16x16x32_bf16 v[122:125], v[156:159], v[182:185], v[122:125]
	v_mfma_f32_16x16x32_bf16 v[110:113], v[148:151], v[190:193], v[110:113]
	v_mfma_f32_16x16x32_bf16 v[106:109], v[156:159], v[190:193], v[106:109]
	v_mfma_f32_16x16x32_bf16 v[94:97], v[148:151], v[198:201], v[94:97]
	v_mfma_f32_16x16x32_bf16 v[90:93], v[156:159], v[198:201], v[90:93]
	v_mfma_f32_16x16x32_bf16 v[78:81], v[148:151], v[206:209], v[78:81]
	v_mfma_f32_16x16x32_bf16 v[74:77], v[156:159], v[206:209], v[74:77]
	v_mfma_f32_16x16x32_bf16 v[126:129], v[152:155], v[186:189], v[126:129]
	v_mfma_f32_16x16x32_bf16 v[122:125], v[160:163], v[186:189], v[122:125]
	v_mfma_f32_16x16x32_bf16 v[110:113], v[152:155], v[194:197], v[110:113]
	v_mfma_f32_16x16x32_bf16 v[106:109], v[160:163], v[194:197], v[106:109]
	v_mfma_f32_16x16x32_bf16 v[94:97], v[152:155], v[202:205], v[94:97]
	v_mfma_f32_16x16x32_bf16 v[90:93], v[160:163], v[202:205], v[90:93]
	v_mfma_f32_16x16x32_bf16 v[78:81], v[152:155], v[210:213], v[78:81]
	v_mfma_f32_16x16x32_bf16 v[74:77], v[160:163], v[210:213], v[74:77]
	v_mfma_f32_16x16x32_bf16 v[118:121], v[166:169], v[182:185], v[118:121]
	v_mfma_f32_16x16x32_bf16 v[114:117], v[174:177], v[182:185], v[114:117]
	v_mfma_f32_16x16x32_bf16 v[102:105], v[166:169], v[190:193], v[102:105]
	v_mfma_f32_16x16x32_bf16 v[98:101], v[174:177], v[190:193], v[98:101]
	v_mfma_f32_16x16x32_bf16 v[86:89], v[166:169], v[198:201], v[86:89]
	v_mfma_f32_16x16x32_bf16 v[82:85], v[174:177], v[198:201], v[82:85]
	v_mfma_f32_16x16x32_bf16 v[70:73], v[166:169], v[206:209], v[70:73]
	v_mfma_f32_16x16x32_bf16 v[66:69], v[174:177], v[206:209], v[66:69]
	v_mfma_f32_16x16x32_bf16 v[118:121], v[170:173], v[186:189], v[118:121]
	v_mfma_f32_16x16x32_bf16 v[114:117], v[178:181], v[186:189], v[114:117]
	v_mfma_f32_16x16x32_bf16 v[102:105], v[170:173], v[194:197], v[102:105]
	v_mfma_f32_16x16x32_bf16 v[98:101], v[178:181], v[194:197], v[98:101]
	v_mfma_f32_16x16x32_bf16 v[86:89], v[170:173], v[202:205], v[86:89]
	v_mfma_f32_16x16x32_bf16 v[82:85], v[178:181], v[202:205], v[82:85]
	v_mfma_f32_16x16x32_bf16 v[70:73], v[170:173], v[210:213], v[70:73]
	v_mfma_f32_16x16x32_bf16 v[66:69], v[178:181], v[210:213], v[66:69]
	s_setprio 0
	s_barrier
	s_add_i32 s54, s54, s34
	v_lshl_add_u64 v[144:145], s[24:25], 0, v[134:135]
	s_mov_b32 m0, s54
	ds_read_b128 v[182:185], v147 offset:16384
	ds_read_b128 v[186:189], v147 offset:17408
	ds_read_b128 v[190:193], v147 offset:18432
	ds_read_b128 v[194:197], v147 offset:19456
	ds_read_b128 v[198:201], v147 offset:20480
	ds_read_b128 v[202:205], v147 offset:21504
	ds_read_b128 v[206:209], v147 offset:22528
	ds_read_b128 v[210:213], v147 offset:23552
	global_load_lds_dwordx4 v[144:145], off
	s_add_i32 m0, s54, 0x2000
	s_add_u32 s54, s24, 0x80000
	v_lshl_add_u64 v[218:219], s[24:25], 0, v[130:131]
	s_addc_u32 s55, s25, 0
	s_add_i32 s57, s57, s34
	global_load_lds_dwordx4 v[218:219], off
	v_lshl_add_u64 v[220:221], s[54:55], 0, v[134:135]
	s_mov_b32 m0, s57
	v_lshl_add_u64 v[226:227], s[26:27], 0, v[132:133]
	global_load_lds_dwordx4 v[220:221], off
	v_lshl_add_u64 v[220:221], s[54:55], 0, v[130:131]
	s_add_i32 m0, s57, 0x2000
	s_nop 0
	global_load_lds_dwordx4 v[220:221], off
	v_lshl_add_u64 v[220:221], s[26:27], 0, v[136:137]
	s_mov_b32 m0, s35
	s_nop 0
	global_load_lds_dwordx4 v[220:221], off
	s_mov_b32 m0, s36
	s_nop 0
	global_load_lds_dwordx4 v[226:227], off
	s_waitcnt vmcnt(8)
	s_waitcnt lgkmcnt(0)
	s_barrier
; #define PG8_STAGE(bufoff, gbase, voff) do { _Pragma("unroll") for (int _i = 0; _i < 2; ++_i) \
;         __builtin_amdgcn_global_load_lds((const unsigned*)((const char*)(gbase) + (voff)[_i]), (PG8_LAS unsigned*)(lds + (bufoff) + ldsw + _i * 8192), 16, 0, 0); } while (0)
; #define PG8_LDA(dst, b, h) do { _Pragma("unroll") for (int m = 0; m < 4; ++m) _Pragma("unroll") for (int k = 0; k < 2; ++k) dst[m][k] = *(const PG8_LAS bf16x8*)(lds + PG8_SA(b, h) + aoff + m * 2048 + k * 1024); } while (0)
; #define PG8_LDB(dst, b, h) do { _Pragma("unroll") for (int n = 0; n < 2; ++n) _Pragma("unroll") for (int k = 0; k < 2; ++k) dst[n][k] = *(const PG8_LAS bf16x8*)(lds + PG8_SB(b, h) + boff + n * 2048 + k * 1024); } while (0)
; #define PG8_MMA(ai, bj, At, Bt) do { __builtin_amdgcn_s_setprio(1); _Pragma("unroll") for (int m = 0; m < 4; ++m) _Pragma("unroll") for (int n = 0; n < 2; ++n) _Pragma("unroll") for (int k = 0; k < 2; ++k) \
;         acc[ai][bj][m][n] = __builtin_amdgcn_mfma_f32_16x16x32_bf16(Bt[n][k], At[m][k], acc[ai][bj][m][n], 0, 0, 0); __builtin_amdgcn_s_setprio(0); } while (0)
; #define PG8_WAIT_V(n) asm volatile("s_waitcnt vmcnt(" #n ")" ::: "memory")
; #define PG8_WAIT_L(n) asm volatile("s_waitcnt lgkmcnt(" #n ")" ::: "memory")
; #define PG8_BAR __builtin_amdgcn_s_barrier()
; #define PG8_SCHED __builtin_amdgcn_sched_barrier(0)
; template <class Epi, class Sched, bool ALIGN_EPI = false, bool SP2 = false>
; __device__ __forceinline__ void gemm_phase(PG8_LAS unsigned char* lds, const Gemm g, const Sched& S, const Epi& E) {
;     ...
;             PG8_WAIT_V(8); PG8_WAIT_L(0); PG8_BAR; PG8_MMA(1, 0, At, B0); PG8_MMA(1, 1, At, B1); PG8_BAR; PG8_SCHED;
;             PG8_LDB(B0, 1, 0); PG8_LDB(B1, 1, 1); PG8_SCHED; PG8_LDA(At, 1, 0); PG8_STAGE(PG8_SA(0, 1), a2 + hstep, voffA);
;             PG8_WAIT_V(8); PG8_WAIT_L(0); PG8_BAR; PG8_MMA(0, 0, At, B0); PG8_MMA(0, 1, At, B1); PG8_BAR; PG8_SCHED;
	s_setprio 1
	s_waitcnt lgkmcnt(0)
	v_mfma_f32_16x16x32_bf16 v[62:65], v[148:151], v[182:185], v[62:65]
	v_mfma_f32_16x16x32_bf16 v[58:61], v[156:159], v[182:185], v[58:61]
	v_mfma_f32_16x16x32_bf16 v[46:49], v[148:151], v[190:193], v[46:49]
	v_mfma_f32_16x16x32_bf16 v[42:45], v[156:159], v[190:193], v[42:45]
	v_mfma_f32_16x16x32_bf16 v[30:33], v[148:151], v[198:201], v[30:33]
	v_mfma_f32_16x16x32_bf16 v[26:29], v[156:159], v[198:201], v[26:29]
	v_mfma_f32_16x16x32_bf16 v[14:17], v[148:151], v[206:209], v[14:17]
	v_mfma_f32_16x16x32_bf16 v[10:13], v[156:159], v[206:209], v[10:13]
	v_mfma_f32_16x16x32_bf16 v[62:65], v[152:155], v[186:189], v[62:65]
	v_mfma_f32_16x16x32_bf16 v[58:61], v[160:163], v[186:189], v[58:61]
	v_mfma_f32_16x16x32_bf16 v[46:49], v[152:155], v[194:197], v[46:49]
	v_mfma_f32_16x16x32_bf16 v[42:45], v[160:163], v[194:197], v[42:45]
	v_mfma_f32_16x16x32_bf16 v[30:33], v[152:155], v[202:205], v[30:33]
	v_mfma_f32_16x16x32_bf16 v[26:29], v[160:163], v[202:205], v[26:29]
	v_mfma_f32_16x16x32_bf16 v[14:17], v[152:155], v[210:213], v[14:17]
	v_mfma_f32_16x16x32_bf16 v[10:13], v[160:163], v[210:213], v[10:13]
	v_mfma_f32_16x16x32_bf16 v[54:57], v[166:169], v[182:185], v[54:57]
	v_mfma_f32_16x16x32_bf16 v[50:53], v[174:177], v[182:185], v[50:53]
	v_mfma_f32_16x16x32_bf16 v[38:41], v[166:169], v[190:193], v[38:41]
	v_mfma_f32_16x16x32_bf16 v[34:37], v[174:177], v[190:193], v[34:37]
	v_mfma_f32_16x16x32_bf16 v[22:25], v[166:169], v[198:201], v[22:25]
	v_mfma_f32_16x16x32_bf16 v[18:21], v[174:177], v[198:201], v[18:21]
	v_mfma_f32_16x16x32_bf16 v[6:9], v[166:169], v[206:209], v[6:9]
	v_mfma_f32_16x16x32_bf16 v[2:5], v[174:177], v[206:209], v[2:5]
	v_mfma_f32_16x16x32_bf16 v[54:57], v[170:173], v[186:189], v[54:57]
	v_mfma_f32_16x16x32_bf16 v[50:53], v[178:181], v[186:189], v[50:53]
	v_mfma_f32_16x16x32_bf16 v[38:41], v[170:173], v[194:197], v[38:41]
	v_mfma_f32_16x16x32_bf16 v[34:37], v[178:181], v[194:197], v[34:37]
	v_mfma_f32_16x16x32_bf16 v[22:25], v[170:173], v[202:205], v[22:25]
	v_mfma_f32_16x16x32_bf16 v[18:21], v[178:181], v[202:205], v[18:21]
	v_mfma_f32_16x16x32_bf16 v[6:9], v[170:173], v[210:213], v[6:9]
	v_mfma_f32_16x16x32_bf16 v[2:5], v[178:181], v[210:213], v[2:5]
	s_setprio 0
	s_barrier
	s_add_i32 s54, 0, 0x18000
	v_add_u32_e32 v143, s54, v146
	s_add_i32 s55, 0, 0x1c000
	ds_read_b128 v[148:151], v143
	ds_read_b128 v[152:155], v143 offset:1024
	ds_read_b128 v[156:159], v143 offset:2048
	ds_read_b128 v[160:163], v143 offset:3072
	v_add_u32_e32 v143, s55, v146
	ds_read_b128 v[166:169], v143
	ds_read_b128 v[170:173], v143 offset:1024
	ds_read_b128 v[174:177], v143 offset:2048
	ds_read_b128 v[178:181], v143 offset:3072
	s_add_u32 s26, s26, 0x80000
	s_addc_u32 s27, s27, 0
	s_mov_b32 m0, s37
	v_lshl_add_u64 v[228:229], s[26:27], 0, v[136:137]
	ds_read_b128 v[182:185], v147 offset:32768
	ds_read_b128 v[186:189], v147 offset:33792
	ds_read_b128 v[190:193], v147 offset:34816
	ds_read_b128 v[194:197], v147 offset:35840
	ds_read_b128 v[198:201], v147 offset:36864
	ds_read_b128 v[202:205], v147 offset:37888
	ds_read_b128 v[206:209], v147 offset:38912
	ds_read_b128 v[210:213], v147 offset:39936
	global_load_lds_dwordx4 v[228:229], off
	v_lshl_add_u64 v[228:229], s[26:27], 0, v[132:133]
	s_mov_b32 m0, s38
	s_nop 0
	global_load_lds_dwordx4 v[228:229], off
	s_waitcnt vmcnt(8)
	s_waitcnt lgkmcnt(0)
	s_barrier
	s_setprio 1
	s_waitcnt lgkmcnt(0)
	v_mfma_f32_16x16x32_bf16 v[126:129], v[148:151], v[182:185], v[126:129]
	v_mfma_f32_16x16x32_bf16 v[122:125], v[156:159], v[182:185], v[122:125]
	v_mfma_f32_16x16x32_bf16 v[110:113], v[148:151], v[190:193], v[110:113]
	v_mfma_f32_16x16x32_bf16 v[106:109], v[156:159], v[190:193], v[106:109]
	v_mfma_f32_16x16x32_bf16 v[94:97], v[148:151], v[198:201], v[94:97]
	v_mfma_f32_16x16x32_bf16 v[90:93], v[156:159], v[198:201], v[90:93]
	v_mfma_f32_16x16x32_bf16 v[78:81], v[148:151], v[206:209], v[78:81]
	v_mfma_f32_16x16x32_bf16 v[74:77], v[156:159], v[206:209], v[74:77]
	v_mfma_f32_16x16x32_bf16 v[126:129], v[152:155], v[186:189], v[126:129]
	v_mfma_f32_16x16x32_bf16 v[122:125], v[160:163], v[186:189], v[122:125]
	v_mfma_f32_16x16x32_bf16 v[110:113], v[152:155], v[194:197], v[110:113]
	v_mfma_f32_16x16x32_bf16 v[106:109], v[160:163], v[194:197], v[106:109]
	v_mfma_f32_16x16x32_bf16 v[94:97], v[152:155], v[202:205], v[94:97]
	v_mfma_f32_16x16x32_bf16 v[90:93], v[160:163], v[202:205], v[90:93]
	v_mfma_f32_16x16x32_bf16 v[78:81], v[152:155], v[210:213], v[78:81]
	v_mfma_f32_16x16x32_bf16 v[74:77], v[160:163], v[210:213], v[74:77]
	v_mfma_f32_16x16x32_bf16 v[118:121], v[166:169], v[182:185], v[118:121]
	v_mfma_f32_16x16x32_bf16 v[114:117], v[174:177], v[182:185], v[114:117]
	v_mfma_f32_16x16x32_bf16 v[102:105], v[166:169], v[190:193], v[102:105]
	v_mfma_f32_16x16x32_bf16 v[98:101], v[174:177], v[190:193], v[98:101]
	v_mfma_f32_16x16x32_bf16 v[86:89], v[166:169], v[198:201], v[86:89]
	v_mfma_f32_16x16x32_bf16 v[82:85], v[174:177], v[198:201], v[82:85]
	v_mfma_f32_16x16x32_bf16 v[70:73], v[166:169], v[206:209], v[70:73]
	v_mfma_f32_16x16x32_bf16 v[66:69], v[174:177], v[206:209], v[66:69]
	v_mfma_f32_16x16x32_bf16 v[118:121], v[170:173], v[186:189], v[118:121]
	v_mfma_f32_16x16x32_bf16 v[114:117], v[178:181], v[186:189], v[114:117]
	v_mfma_f32_16x16x32_bf16 v[102:105], v[170:173], v[194:197], v[102:105]
	v_mfma_f32_16x16x32_bf16 v[98:101], v[178:181], v[194:197], v[98:101]
	v_mfma_f32_16x16x32_bf16 v[86:89], v[170:173], v[202:205], v[86:89]
	v_mfma_f32_16x16x32_bf16 v[82:85], v[178:181], v[202:205], v[82:85]
	v_mfma_f32_16x16x32_bf16 v[70:73], v[170:173], v[210:213], v[70:73]
	v_mfma_f32_16x16x32_bf16 v[66:69], v[178:181], v[210:213], v[66:69]
	s_setprio 0
	s_barrier
; #define PG8_STAGE(bufoff, gbase, voff) do { _Pragma("unroll") for (int _i = 0; _i < 2; ++_i) \
;         __builtin_amdgcn_global_load_lds((const unsigned*)((const char*)(gbase) + (voff)[_i]), (PG8_LAS unsigned*)(lds + (bufoff) + ldsw + _i * 8192), 16, 0, 0); } while (0)
; #define PG8_LDA(dst, b, h) do { _Pragma("unroll") for (int m = 0; m < 4; ++m) _Pragma("unroll") for (int k = 0; k < 2; ++k) dst[m][k] = *(const PG8_LAS bf16x8*)(lds + PG8_SA(b, h) + aoff + m * 2048 + k * 1024); } while (0)
; #define PG8_MMA(ai, bj, At, Bt) do { __builtin_amdgcn_s_setprio(1); _Pragma("unroll") for (int m = 0; m < 4; ++m) _Pragma("unroll") for (int n = 0; n < 2; ++n) _Pragma("unroll") for (int k = 0; k < 2; ++k) \
;         acc[ai][bj][m][n] = __builtin_amdgcn_mfma_f32_16x16x32_bf16(Bt[n][k], At[m][k], acc[ai][bj][m][n], 0, 0, 0); __builtin_amdgcn_s_setprio(0); } while (0)
; #define PG8_WAIT_V(n) asm volatile("s_waitcnt vmcnt(" #n ")" ::: "memory")
; #define PG8_WAIT_L(n) asm volatile("s_waitcnt lgkmcnt(" #n ")" ::: "memory")
; #define PG8_BAR __builtin_amdgcn_s_barrier()
; #define PG8_SCHED __builtin_amdgcn_sched_barrier(0)
; template <class Epi, class Sched, bool ALIGN_EPI = false, bool SP2 = false>
; __device__ __forceinline__ void gemm_phase(PG8_LAS unsigned char* lds, const Gemm g, const Sched& S, const Epi& E) {
;     ...
;         for (int t = 0; t < nt; t += 2) {
;     ...
;             PG8_LDA(At, 1, 1); PG8_STAGE(PG8_SB(1, 0), b3, voffB); PG8_STAGE(PG8_SB(1, 1), b3 + hstep, voffB); PG8_STAGE(PG8_SA(1, 0), a3, voffA);
;             PG8_WAIT_V(8); PG8_WAIT_L(0); PG8_BAR; PG8_MMA(1, 0, At, B0); PG8_MMA(1, 1, At, B1); PG8_BAR; PG8_SCHED;
	s_add_i32 s26, s54, s34
	v_lshl_add_u64 v[144:145], v[144:145], 0, s[84:85]
	s_mov_b32 m0, s26
	ds_read_b128 v[182:185], v147 offset:49152
	ds_read_b128 v[186:189], v147 offset:50176
	ds_read_b128 v[190:193], v147 offset:51200
	ds_read_b128 v[194:197], v147 offset:52224
	ds_read_b128 v[198:201], v147 offset:53248
	ds_read_b128 v[202:205], v147 offset:54272
	ds_read_b128 v[206:209], v147 offset:55296
	ds_read_b128 v[210:213], v147 offset:56320
	global_load_lds_dwordx4 v[144:145], off
	s_add_i32 m0, s26, 0x2000
	s_add_u32 s24, s24, 0x80080
	v_lshl_add_u64 v[144:145], v[218:219], 0, s[84:85]
	s_addc_u32 s25, s25, 0
	s_add_i32 s26, s55, s34
	global_load_lds_dwordx4 v[144:145], off
	v_lshl_add_u64 v[144:145], s[24:25], 0, v[134:135]
	s_mov_b32 m0, s26
	s_nop 0
	global_load_lds_dwordx4 v[144:145], off
	v_lshl_add_u64 v[144:145], s[24:25], 0, v[130:131]
	s_add_i32 m0, s26, 0x2000
	s_nop 0
	global_load_lds_dwordx4 v[144:145], off
	v_lshl_add_u64 v[144:145], v[220:221], 0, s[84:85]
	s_mov_b32 m0, s40
	s_nop 0
	global_load_lds_dwordx4 v[144:145], off
	v_lshl_add_u64 v[144:145], v[226:227], 0, s[84:85]
	s_mov_b32 m0, s41
	s_nop 0
	global_load_lds_dwordx4 v[144:145], off
	s_waitcnt vmcnt(8)
	s_waitcnt lgkmcnt(0)
	s_barrier
	s_setprio 1
	s_waitcnt lgkmcnt(0)
	v_mfma_f32_16x16x32_bf16 v[62:65], v[148:151], v[182:185], v[62:65]
	v_mfma_f32_16x16x32_bf16 v[58:61], v[156:159], v[182:185], v[58:61]
	v_mfma_f32_16x16x32_bf16 v[46:49], v[148:151], v[190:193], v[46:49]
	v_mfma_f32_16x16x32_bf16 v[42:45], v[156:159], v[190:193], v[42:45]
	v_mfma_f32_16x16x32_bf16 v[30:33], v[148:151], v[198:201], v[30:33]
	v_mfma_f32_16x16x32_bf16 v[26:29], v[156:159], v[198:201], v[26:29]
	v_mfma_f32_16x16x32_bf16 v[14:17], v[148:151], v[206:209], v[14:17]
	v_mfma_f32_16x16x32_bf16 v[10:13], v[156:159], v[206:209], v[10:13]
	v_mfma_f32_16x16x32_bf16 v[62:65], v[152:155], v[186:189], v[62:65]
	v_mfma_f32_16x16x32_bf16 v[58:61], v[160:163], v[186:189], v[58:61]
	v_mfma_f32_16x16x32_bf16 v[46:49], v[152:155], v[194:197], v[46:49]
	v_mfma_f32_16x16x32_bf16 v[42:45], v[160:163], v[194:197], v[42:45]
	v_mfma_f32_16x16x32_bf16 v[30:33], v[152:155], v[202:205], v[30:33]
	v_mfma_f32_16x16x32_bf16 v[26:29], v[160:163], v[202:205], v[26:29]
	v_mfma_f32_16x16x32_bf16 v[14:17], v[152:155], v[210:213], v[14:17]
	v_mfma_f32_16x16x32_bf16 v[10:13], v[160:163], v[210:213], v[10:13]
	v_mfma_f32_16x16x32_bf16 v[54:57], v[166:169], v[182:185], v[54:57]
	v_mfma_f32_16x16x32_bf16 v[50:53], v[174:177], v[182:185], v[50:53]
	v_mfma_f32_16x16x32_bf16 v[38:41], v[166:169], v[190:193], v[38:41]
	v_mfma_f32_16x16x32_bf16 v[34:37], v[174:177], v[190:193], v[34:37]
	v_mfma_f32_16x16x32_bf16 v[22:25], v[166:169], v[198:201], v[22:25]
	v_mfma_f32_16x16x32_bf16 v[18:21], v[174:177], v[198:201], v[18:21]
	v_mfma_f32_16x16x32_bf16 v[6:9], v[166:169], v[206:209], v[6:9]
	v_mfma_f32_16x16x32_bf16 v[2:5], v[174:177], v[206:209], v[2:5]
	v_mfma_f32_16x16x32_bf16 v[54:57], v[170:173], v[186:189], v[54:57]
	v_mfma_f32_16x16x32_bf16 v[50:53], v[178:181], v[186:189], v[50:53]
	v_mfma_f32_16x16x32_bf16 v[38:41], v[170:173], v[194:197], v[38:41]
	v_mfma_f32_16x16x32_bf16 v[34:37], v[178:181], v[194:197], v[34:37]
	v_mfma_f32_16x16x32_bf16 v[22:25], v[170:173], v[202:205], v[22:25]
	v_mfma_f32_16x16x32_bf16 v[18:21], v[178:181], v[202:205], v[18:21]
	v_mfma_f32_16x16x32_bf16 v[6:9], v[170:173], v[210:213], v[6:9]
	v_mfma_f32_16x16x32_bf16 v[2:5], v[178:181], v[210:213], v[2:5]
	s_setprio 0
	s_barrier
	s_add_i32 s52, s52, 2
	s_add_u32 s6, s6, 0x100
	s_addc_u32 s7, s7, 0
	s_add_u32 s47, s47, 0x100
	s_addc_u32 s51, s51, 0
	s_cmp_gt_u32 s52, 29
	s_cbranch_scc0 .LBB0_268
	s_and_b64 vcc, exec, s[10:11]
	s_cbranch_vccz .LBB0_271
	s_barrier
